# v34 + XCD leader leaves the barrier without waiting for its release atomic; kernel-start sync without the (no-op) L1 invalidate
# speedup vs baseline: 1.0507x; 1.0010x over previous
; #define LAS __attribute__((address_space(3)))
; __device__ __forceinline__ TItem titem(const Args& a, int it) {
;     constexpr int I0 = (DM / 64) * (INC / 256), I1 = (512 / 64) * (512 / 256), I2 = (512 / 64) * (1024 / 256), I3 = I2, I4 = (DM / 64) * (DM / 256), I5 = (DM / 64) * (FF / 256), I6 = (FF / 64) * (DM / 256);
;     constexpr int IL = I0 + I1 + I2 + I3 + I4 + I5 + I6;
;     const int l = it / IL; int r = it % IL; bf16_t* Wl = (bf16_t*)(a.ws + WS_W) + (size_t)l * W_LAYER; TItem t;
;     if (r < I0) { t.W = a.in[I_WIN] + (size_t)l * DM * INC; t.gain = a.in[I_N1G] + l * DM; t.WT = Wl + W_IN; t.K = DM; t.N = INC; }
;     else if ((r -= I0) < I1) { t.W = a.in[I_WGLU] + (size_t)l * 512 * 512; t.gain = nullptr; t.WT = Wl + W_GLU; t.K = 512; t.N = 512; }
;     else if ((r -= I1) < I2) { t.W = a.in[I_WAO] + (size_t)l * 512 * 1024; t.gain = nullptr; t.WT = Wl + W_AO; t.K = 512; t.N = 1024; }
;     else if ((r -= I2) < I3) { t.W = a.in[I_WSO] + (size_t)l * 512 * 1024; t.gain = nullptr; t.WT = Wl + W_SO; t.K = 512; t.N = 1024; }
;     else if ((r -= I3) < I4) { t.W = a.in[I_WOUT] + (size_t)l * DM * DM; t.gain = nullptr; t.WT = Wl + W_OUT; t.K = DM; t.N = DM; }
;     else if ((r -= I4) < I5) { t.W = a.in[I_WUP] + (size_t)l * DM * FF; t.gain = a.in[I_N2G] + l * DM; t.WT = Wl + W_UP; t.K = DM; t.N = FF; }
;     else { r -= I5; t.W = a.in[I_WDN] + (size_t)l * FF * DM; t.gain = nullptr; t.WT = Wl + W_DN; t.K = FF; t.N = DM; }
;     const int nblk = t.N / 256; t.k0 = 64 * (r / nblk); t.n0 = 256 * (r % nblk);
;     return t;
; }
; __device__ __forceinline__ void prologue(const Args& a, LAS unsigned char* lds, int tid, int wave, int lane) {
;     unsigned char* ws = a.ws;
;     const int gw = blockIdx.x * 8 + wave, NGW = gridDim.x * 8;
;     {   constexpr int TS = 257; LAS float* tile = (LAS float*)lds;
;         f32x4 v[8]; int it = blockIdx.x;
;         if (it < T_ITEMS) { const TItem t = titem(a, it);
; #pragma unroll
;             for (int i = 0; i < 8; ++i) { v[i] = __builtin_nontemporal_load((const f32x4*)(t.W + (size_t)(t.k0 + 8 * wave + i) * t.N + t.n0 + 4 * lane)); if (t.gain) v[i] = v[i] * t.gain[t.k0 + 8 * wave + i]; } }
.LBB0_12:
.LBB0_13:
	s_or_b64 exec, exec, s[14:15]
	s_load_dwordx16 s[12:27], s[0:1], 0x0
	s_lshr_b32 s94, s59, 6
	v_mov_b32_e32 v33, v184
	v_mov_b32_e32 v31, 0
	s_cmpk_lt_i32 s2, 0x6c0
	s_waitcnt lgkmcnt(0)
	v_writelane_b32 v252, s12, 0
	v_mov_b32_e32 v30, v31
	v_mov_b32_e32 v29, v31
	v_writelane_b32 v252, s13, 1
	v_writelane_b32 v252, s14, 2
	v_writelane_b32 v252, s15, 3
	v_writelane_b32 v252, s16, 4
	v_writelane_b32 v252, s17, 5
	v_writelane_b32 v252, s18, 6
	v_writelane_b32 v252, s19, 7
	v_writelane_b32 v252, s20, 8
	v_writelane_b32 v252, s21, 9
	v_writelane_b32 v252, s22, 10
	v_writelane_b32 v252, s23, 11
	v_writelane_b32 v252, s24, 12
	v_writelane_b32 v252, s25, 13
	v_writelane_b32 v252, s26, 14
	v_writelane_b32 v252, s27, 15
	s_load_dwordx16 s[72:87], s[0:1], 0x40
	s_load_dwordx16 s[12:27], s[0:1], 0x80
	s_barrier
	s_waitcnt lgkmcnt(0)
	v_mov_b32_e32 v28, v31
	v_writelane_b32 v252, s12, 16
	v_and_b32_e32 v32, 63, v33
	v_mov_b32_e32 v27, v31
	v_writelane_b32 v252, s13, 17
	v_writelane_b32 v252, s14, 18
	v_writelane_b32 v252, s15, 19
	v_writelane_b32 v252, s16, 20
	v_writelane_b32 v252, s17, 21
	v_writelane_b32 v252, s18, 22
	v_writelane_b32 v252, s19, 23
	v_writelane_b32 v252, s20, 24
	v_writelane_b32 v252, s21, 25
	v_writelane_b32 v252, s22, 26
	v_writelane_b32 v252, s23, 27
	v_writelane_b32 v252, s24, 28
	v_writelane_b32 v252, s25, 29
	v_writelane_b32 v252, s26, 30
	v_writelane_b32 v252, s27, 31
	s_cselect_b64 s[12:13], -1, 0
	s_cmpk_gt_i32 s2, 0x6bf
	v_mov_b32_e32 v26, v31
	v_mov_b32_e32 v25, v31
	v_mov_b32_e32 v24, v31
	v_mov_b32_e32 v23, v31
	v_mov_b32_e32 v22, v31
	v_mov_b32_e32 v21, v31
	v_mov_b32_e32 v20, v31
	v_mov_b32_e32 v19, v31
	v_mov_b32_e32 v18, v31
	v_mov_b32_e32 v17, v31
	v_mov_b32_e32 v16, v31
	v_mov_b32_e32 v15, v31
	v_mov_b32_e32 v14, v31
	v_mov_b32_e32 v13, v31
	v_mov_b32_e32 v12, v31
	v_mov_b32_e32 v11, v31
	v_mov_b32_e32 v10, v31
	v_mov_b32_e32 v9, v31
	v_mov_b32_e32 v8, v31
	v_mov_b32_e32 v7, v31
	v_mov_b32_e32 v6, v31
	v_mov_b32_e32 v5, v31
	v_mov_b32_e32 v4, v31
	v_mov_b32_e32 v3, v31
	v_mov_b32_e32 v2, v31
	v_mov_b32_e32 v1, v31
	v_mov_b32_e32 v0, v31
	s_cbranch_scc1 .LBB0_63
	s_mul_hi_i32 s0, s2, 0x4bda12f7
	s_lshr_b32 s1, s0, 31
	s_ashr_i32 s0, s0, 8
	s_add_i32 s0, s0, s1
	s_mul_i32 s1, s0, 0x360
	s_sub_i32 s22, s2, s1
	s_ashr_i32 s1, s0, 31
	s_cmpk_gt_i32 s22, 0xcf
	s_cbranch_scc0 .LBB0_28
	s_cmpk_gt_u32 s22, 0xdf
	s_cbranch_scc0 .LBB0_29
	s_cmpk_gt_u32 s22, 0xff
	s_cbranch_scc0 .LBB0_30
	s_cmpk_gt_u32 s22, 0x11f
	s_cbranch_scc0 .LBB0_31
	s_cmpk_gt_u32 s22, 0x15f
	s_cbranch_scc0 .LBB0_32
	s_lshl_b64 s[20:21], s[0:1], 24
	s_cmpk_gt_u32 s22, 0x25f
	s_cbranch_scc0 .LBB0_33
	s_add_i32 s23, s22, 0xfffffda0
	s_add_u32 s18, s10, s20
	s_addc_u32 s19, s11, s21
	s_mov_b64 s[14:15], 0
	s_branch .LBB0_34

; #define LAS __attribute__((address_space(3)))
; __device__ __forceinline__ int opq(int v) { asm volatile("" : "+v"(v)); return v; }
; #define GRID_BAR() do { XcdBarrier b_; b_.bar = (unsigned*)(a.ws + 16384); b_.x = xb_xcc_id(); b_.st = (volatile LAS unsigned*)(lds + LDS_BYTES - 64); xcd_barrier(b_); } while (0)
; __global__ void __launch_bounds__(512, 2) mk_fwd(Args a) {
;     ...
;     const int tid = threadIdx.x, lane = tid & 63, wave = __builtin_amdgcn_readfirstlane(tid >> 6);
;     const int G = gridDim.x, bx = blockIdx.x;
;     unsigned char* ws = a.ws;
;     float* ss = (float*)(ws + WS_SS);
;     bf16_t* bufA = (bf16_t*)(ws + WS_A);
;     bf16_t* mixed = (bf16_t*)a.out;
;     bf16_t* attn = (bf16_t*)(ws + WS_B); bf16_t* ssmy = (bf16_t*)(ws + WS_B + HALFROWS); bf16_t* xb2 = (bf16_t*)(ws + WS_B);
;     bf16_t* Z = (bf16_t*)(ws + WS_C); bf16_t* ssmg = (bf16_t*)(ws + WS_C + ZBYTES); float* Ebuf = (float*)(ws + WS_C + ZBYTES + HALFROWS); bf16_t* H = (bf16_t*)(ws + WS_C);
;     unsigned* barw = (unsigned*)(ws + 16384);
;     volatile LAS unsigned* bst = (volatile LAS unsigned*)(lds + LDS_BYTES - 64);
;     if (bx == 0) for (int i = tid; i < XCD_BAR_WORDS; i += 512) barw[i] = 0u;
;     if (tid < 2) bst[tid] = 0u;
;     __syncthreads();
;     grid.sync();
;     { const int t2 = opq(threadIdx.x); prologue(a, lds, t2, wave, t2 & 63); }
;     (void)xcd_barrier_post(barw, bst);
;     ...
;     GRID_BAR();
; #pragma unroll 1
;     for (int l = 0; l < 2; ++l) {
;         const bf16_t* Wl = (const bf16_t*)(ws + WS_W) + (size_t)l * W_LAYER;
;         float* ss1 = ss + (size_t)(2 * l) * MTOK; float* ss2 = ss + (size_t)(2 * l + 1) * MTOK; float* ss1n = ss + (size_t)(2 * l + 2) * MTOK;
;         { pg8::Gemm g{bufA, Wl + W_IN, NTOK_P, INC - 256, DM}; pg8::StaticOrder S; S.init(NTOK_P, INC - 256, G, bx); EpiIn E{Z, ss1, a.in[I_BG] + l * 2048, 0};
.LBB0_204:
	s_or_b64 exec, exec, s[8:9]
.LBB0_205:
	v_writelane_b32 v252, s88, 34
	s_nop 1
	v_writelane_b32 v252, s89, 35
	v_writelane_b32 v252, s66, 36
	s_nop 1
	v_writelane_b32 v252, s67, 37
	v_writelane_b32 v252, s72, 38
	s_nop 1
	v_writelane_b32 v252, s73, 39
	v_writelane_b32 v252, s74, 40
	v_writelane_b32 v252, s75, 41
	v_writelane_b32 v252, s76, 42
	v_writelane_b32 v252, s77, 43
	v_writelane_b32 v252, s78, 44
	v_writelane_b32 v252, s79, 45
	v_writelane_b32 v252, s80, 46
	v_writelane_b32 v252, s81, 47
	v_writelane_b32 v252, s82, 48
	v_writelane_b32 v252, s83, 49
	v_writelane_b32 v252, s84, 50
	v_writelane_b32 v252, s85, 51
	v_writelane_b32 v252, s86, 52
	v_writelane_b32 v252, s87, 53
	s_or_b64 exec, exec, s[0:1]
	s_add_u32 s36, s70, 0x5a00000
	s_addc_u32 s37, s71, 0
	s_add_u32 s40, s70, 0x6a80000
	s_addc_u32 s41, s71, 0
	s_add_u32 s48, s70, 0x7b00000
	s_addc_u32 s49, s71, 0
	s_add_u32 s50, s70, 0xe640000
	s_addc_u32 s51, s71, 0
	s_add_u32 s0, s70, 0xf6c0000
	s_addc_u32 s1, s71, 0
	v_writelane_b32 v252, s0, 54
	s_waitcnt vmcnt(2)
	v_and_b32_e32 v20, 7, v184
	v_mov_b32_e32 v1, 0
	v_writelane_b32 v252, s1, 55
	s_add_u32 s0, s70, 0x300000
	v_writelane_b32 v252, s0, 56
	s_addc_u32 s0, s71, 0
	s_cmpk_lt_i32 s2, 0x300
	v_writelane_b32 v252, s0, 57
	s_cselect_b64 s[0:1], -1, 0
	v_writelane_b32 v252, s0, 58
	s_ashr_i32 s33, s2, 31
	s_ashr_i32 s3, s34, 31
	v_writelane_b32 v252, s1, 59
	s_lshr_b32 s0, s33, 29
	s_add_i32 s0, s2, s0
	s_ashr_i32 s6, s0, 3
	s_and_b32 s0, s0, -8
	s_sub_i32 s0, s2, s0
	s_add_i32 s1, s34, s2
	s_add_u32 s28, s70, 0x4200
	s_addc_u32 s29, s71, 0
	s_add_u32 s46, s70, 0x4400
	s_addc_u32 s47, s71, 0
	s_add_u32 s4, s70, 0x4500
	s_addc_u32 s5, s71, 0
	v_writelane_b32 v252, s4, 60
	s_mul_i32 s13, s0, 17
	v_mov_b32_e32 v6, v1
	v_writelane_b32 v252, s5, 61
	s_add_u32 s4, s70, 0x4600
	s_addc_u32 s5, s71, 0
	v_writelane_b32 v252, s4, 62
	v_mov_b32_e32 v7, v1
	v_mov_b32_e32 v2, v1
	v_writelane_b32 v252, s5, 63
	s_add_u32 s4, s70, 0x4700
	s_addc_u32 s5, s71, 0
	v_writelane_b32 v253, s4, 0
	v_mov_b32_e32 v3, v1
	v_mov_b32_e32 v4, v1
	v_writelane_b32 v253, s5, 1
	s_add_u32 s4, s70, 0x4800
	s_addc_u32 s5, s71, 0
	v_writelane_b32 v253, s4, 2
	v_mov_b32_e32 v5, v1
	v_mbcnt_hi_u32_b32 v216, -1, v8
	v_writelane_b32 v253, s5, 3
	s_add_u32 s4, s70, 0x4900
	s_addc_u32 s5, s71, 0
	v_writelane_b32 v253, s4, 4
	s_mov_b32 s27, 0
	v_mov_b32_e32 v185, 0x358637bd
	v_writelane_b32 v253, s5, 5
	s_add_u32 s4, s70, 0x4a00
	s_addc_u32 s5, s71, 0
	v_writelane_b32 v253, s4, 6
	v_mov_b32_e32 v214, 0xc0135761
	v_mov_b32_e32 v215, 0x1a00
	v_writelane_b32 v253, s5, 7
	s_add_u32 s4, s70, 0x4b00
	s_addc_u32 s5, s71, 0
	v_writelane_b32 v253, s4, 8
	v_mov_b64_e32 v[212:213], 0x100
	v_mov_b64_e32 v[218:219], 0xff
	v_writelane_b32 v253, s5, 9
	s_add_u32 s4, s70, 0x4c00
	s_addc_u32 s5, s71, 0
	v_writelane_b32 v253, s4, 10
	s_movk_i32 s79, 0x200
	s_movk_i32 s80, 0x400
	v_writelane_b32 v253, s5, 11
	s_add_u32 s4, s70, 0x4d00
	s_addc_u32 s5, s71, 0
	v_writelane_b32 v253, s4, 12
	s_movk_i32 s81, 0x81
	s_mov_b32 s73, 0x10000
	v_writelane_b32 v253, s5, 13
	s_add_u32 s4, s70, 0x4e00
	s_addc_u32 s5, s71, 0
	v_writelane_b32 v253, s4, 14
	s_movk_i32 s84, 0x4000
	s_mov_b32 s85, 0x8000
	v_writelane_b32 v253, s5, 15
	s_add_u32 s4, s70, 0x4f00
	s_addc_u32 s5, s71, 0
	v_writelane_b32 v253, s4, 16
	s_mov_b32 s72, 0xc000
	s_mov_b32 s86, 0x800000
	v_writelane_b32 v253, s5, 17
	s_add_u32 s4, s70, 0x5000
	s_addc_u32 s5, s71, 0
	v_writelane_b32 v253, s4, 18
	s_movk_i32 s87, 0x1a00
	s_movk_i32 s88, 0x90
	v_writelane_b32 v253, s5, 19
	s_add_u32 s4, s70, 0x5100
	s_addc_u32 s5, s71, 0
	v_writelane_b32 v253, s4, 20
	s_movk_i32 s89, 0x4ff
	s_movk_i32 s90, 0x110
	v_writelane_b32 v253, s5, 21
	s_add_u32 s4, s70, 0x5200
	s_addc_u32 s5, s71, 0
	v_writelane_b32 v253, s4, 22
	s_movk_i32 s91, 0x210
	s_mov_b32 s92, 0xefa18f08
	v_writelane_b32 v253, s5, 23
	s_add_u32 s4, s70, 0x5300
	s_addc_u32 s5, s71, 0
	v_writelane_b32 v253, s4, 24
	s_mov_b32 s42, s27
	s_waitcnt lgkmcnt(0)
	v_writelane_b32 v253, s5, 25
	s_add_u32 s4, s70, 0x7400
	s_addc_u32 s5, s71, 0
	v_writelane_b32 v253, s4, 26
	s_barrier
	s_nop 0
	v_writelane_b32 v253, s5, 27
	s_add_u32 s4, s70, 0x7500
	s_addc_u32 s5, s71, 0
	v_writelane_b32 v253, s4, 28
	s_cmpk_lt_i32 s2, 0x100
	s_nop 0
	v_writelane_b32 v253, s5, 29
	s_cselect_b64 s[4:5], -1, 0
	v_writelane_b32 v253, s4, 30
	s_nop 1
	v_writelane_b32 v253, s5, 31
	s_add_u32 s4, s68, 0x4200000
	s_addc_u32 s5, s69, 0
	v_writelane_b32 v253, s4, 32
	s_nop 1
	v_writelane_b32 v253, s5, 33
	s_add_u32 s4, s68, 0x4300000
	s_addc_u32 s5, s69, 0
	v_writelane_b32 v253, s4, 34
	s_nop 1
	v_writelane_b32 v253, s5, 35
	s_and_b32 s4, s62, 24
	s_add_u32 s8, s70, 0x180000
	s_addc_u32 s9, s71, 0
	v_writelane_b32 v253, s8, 36
	s_add_i32 s5, s94, s4
	s_add_u32 s4, s70, 0x200000
	v_writelane_b32 v253, s9, 37
	v_writelane_b32 v253, s4, 38
	s_addc_u32 s4, s71, 0
	v_writelane_b32 v253, s4, 39
	s_cmpk_lt_i32 s2, 0xe0
	s_mul_i32 s4, s94, 0x2100
	s_cselect_b64 s[8:9], -1, 0
	s_add_i32 s76, s4, 0
	s_mul_i32 s4, s94, 0xffffdf20
	v_writelane_b32 v253, s8, 40
	s_add_i32 s95, s76, s4
	s_add_u32 s4, s70, 0x1a0000
	v_writelane_b32 v253, s9, 41
	v_writelane_b32 v253, s4, 42
	s_addc_u32 s4, s71, 0
	v_writelane_b32 v253, s4, 43
	v_writelane_b32 v253, s5, 44
	s_lshl_b32 s4, s5, 4
	v_writelane_b32 v253, s4, 45
	s_mul_i32 s4, s94, 0x1100
	s_add_i32 s77, s4, 0
	s_add_i32 s77, s77, 0x14c00
	s_lshl_b32 s4, s94, 4
	s_cmpk_lt_i32 s2, 0x200
	v_writelane_b32 v253, s4, 46
	s_cselect_b64 s[4:5], -1, 0
	v_writelane_b32 v253, s4, 47
	s_lshl_b32 s10, s0, 4
	s_add_i32 s7, s1, 0xffffff80
	v_writelane_b32 v253, s5, 48
	s_and_b32 s4, s59, 0xffffffc0
;     __host__ __device__ bool next(int i, Unit& u) const {
;         const long L = (long)i * G + c; if (L >= nwg) return false;
;         int wgid = (int)L; { const int q = nwg / NXCD, r = nwg % NXCD, xcd = wgid % NXCD, off = wgid / NXCD; wgid = (xcd < r ? xcd * (q + 1) : r * (q + 1) + (xcd - r) * q) + off; }
;         const int nig = WGM * nN, gid = wgid / nig, fm = gid * WGM, gsz = (nM - fm) < WGM ? (nM - fm) : WGM;
;         u.pm = fm + ((wgid % nig) % gsz); u.pn = (wgid % nig) / gsz; return true;
;     }
; template <class Epi, class Sched, bool ALIGN_EPI = false, bool SP2 = false>
; __device__ __forceinline__ void gemm_phase(PG8_LAS unsigned char* lds, const Gemm g, const Sched& S, const Epi& E) {
;     ...
;     const char* cA = (const char*)g.A + (size_t)cur.pm * tstep; const char* cB = (const char*)g.Bt + (size_t)cur.pn * tstep;
	s_cmpk_lg_i32 s34, 0x100
	v_writelane_b32 v253, s4, 49
	s_cselect_b64 s[4:5], -1, 0
	v_writelane_b32 v253, s4, 50
	s_add_i32 s11, s2, 0x80
	s_nop 0
	v_writelane_b32 v253, s5, 51
	s_sub_i32 s5, s34, s2
	s_add_i32 s4, s5, 0xff
	s_cmpk_lt_i32 s2, 0x80
	s_cselect_b64 s[8:9], -1, 0
	v_cndmask_b32_e64 v0, 0, 1, s[8:9]
	v_writelane_b32 v253, s8, 52
	s_nop 1
	v_writelane_b32 v253, s9, 53
	s_and_b64 s[8:9], s[8:9], exec
	s_cselect_b32 s11, s11, -1
	s_add_i32 s12, s2, 0xffffff40
	s_add_u32 s8, s68, 0x4440000
	v_writelane_b32 v253, s8, 54
	s_addc_u32 s8, s69, 0
	v_writelane_b32 v253, s8, 55
	s_add_u32 s8, s68, 0x5440000
	v_writelane_b32 v253, s8, 56
	s_addc_u32 s8, s69, 0
	v_writelane_b32 v253, s8, 57
	s_add_u32 s8, s70, 0x7b00a00
	s_addc_u32 s9, s71, 0
	v_writelane_b32 v253, s8, 58
	s_nop 1
	v_writelane_b32 v253, s9, 59
	s_lshl_b32 s8, s0, 5
	s_add_u32 s14, s70, 0x7b01200
	s_addc_u32 s15, s71, 0
	v_writelane_b32 v253, s14, 60
	s_cmpk_lt_i32 s2, 0x400
	s_nop 0
	v_writelane_b32 v253, s15, 61
	s_cselect_b64 s[14:15], -1, 0
	s_lshl_b32 s9, s0, 7
	s_cmp_lt_i32 s0, 0
	s_cselect_b32 s10, s13, s10
	s_mul_i32 s13, s0, 33
	s_cselect_b32 s13, s13, s8
	s_movk_i32 s8, 0x61
	s_cselect_b32 s8, s8, 0x60
	v_writelane_b32 v253, s14, 62
	s_mul_i32 s8, s0, s8
	s_mulk_i32 s0, 0x81
	v_writelane_b32 v253, s15, 63
	s_cselect_b32 s14, s0, s9
	s_add_i32 s8, s8, s6
	s_mul_hi_i32 s0, s8, 0x2aaaaaab
	s_lshr_b32 s9, s0, 31
	s_ashr_i32 s0, s0, 4
	s_add_i32 s0, s0, s9
	s_mul_i32 s9, s0, 0x60
	s_sub_i32 s8, s8, s9
	s_bfe_i32 s9, s8, 0x80000
	s_bfe_u32 s9, s9, 0x3000c
	s_add_i32 s9, s8, s9
	s_and_b32 s15, s9, 0xf8
	s_add_i32 s10, s10, s6
	s_sub_i32 s8, s8, s15
	s_ashr_i32 s15, s10, 31
	s_lshr_b32 s15, s15, 28
	s_add_i32 s15, s10, s15
	s_and_b32 s16, s15, 0xfff0
	s_sub_i32 s10, s10, s16
	s_bfe_i32 s16, s10, 0x80000
	s_bfe_u32 s16, s16, 0x3000c
	s_add_i32 s16, s10, s16
	s_and_b32 s17, s16, 0xf8
	s_lshl_b32 s0, s0, 3
	s_sext_i32_i8 s8, s8
	s_sub_i32 s10, s10, s17
	s_bfe_i32 s9, s9, 0x80000
	s_add_i32 s18, s0, s8
	s_ashr_i32 s0, s15, 4
	s_bfe_i32 s8, s16, 0x80000
	s_sext_i32_i16 s17, s9
	s_lshl_b32 s0, s0, 3
	s_sext_i32_i16 s8, s8
	s_sext_i32_i8 s9, s10
	s_add_i32 s20, s0, s9
	s_ashr_i32 s0, s8, 3
	v_writelane_b32 v254, s0, 0
	s_lshr_b32 s0, s8, 3
	s_bfe_i64 s[8:9], s[0:1], 0x100000
	s_lshl_b64 s[8:9], s[8:9], 18
	v_writelane_b32 v254, s8, 1
	s_ashr_i32 s0, s17, 3
	s_ashr_i32 s21, s20, 31
	v_writelane_b32 v254, s9, 2
	v_writelane_b32 v254, s0, 3
	s_mov_b32 s8, s20
	v_writelane_b32 v254, s8, 4
	s_lshr_b32 s0, s17, 3
	s_nop 0
	v_writelane_b32 v254, s9, 5
	s_lshl_b64 s[8:9], s[20:21], 18
	s_add_u32 s8, s40, s8
	s_addc_u32 s9, s41, s9
	s_add_u32 s16, s8, 0x20000
	v_writelane_b32 v254, s8, 6
	s_addc_u32 s17, s9, 0
	s_cmpk_gt_i32 s2, 0xbf
	v_writelane_b32 v254, s9, 7
	v_writelane_b32 v254, s16, 8
	s_cselect_b32 s8, s12, s11
	s_nop 0
	v_writelane_b32 v254, s17, 9
	v_writelane_b32 v254, s8, 10
	v_readfirstlane_b32 s8, v0
	s_cselect_b32 s8, 2, s8
	v_cvt_f32_u32_e32 v0, s34
	v_writelane_b32 v254, s8, 11
	s_cselect_b32 s8, 64, 1
	v_writelane_b32 v254, s8, 12
	s_add_i32 s8, s13, s6
	s_ashr_i32 s9, s8, 31
	s_lshr_b32 s9, s9, 27
	s_add_i32 s9, s8, s9
	s_and_b32 s10, s9, 0xffe0
	s_sub_i32 s8, s8, s10
	s_bfe_i32 s10, s8, 0x80000
	s_bfe_u32 s10, s10, 0x3000c
	s_add_i32 s10, s8, s10
	s_and_b32 s11, s10, 0xf8
	s_sub_i32 s8, s8, s11
	s_ashr_i32 s9, s9, 5
	s_bfe_i32 s10, s10, 0x80000
	s_lshl_b32 s9, s9, 3
	s_sext_i32_i16 s10, s10
	s_sext_i32_i8 s8, s8
	s_add_i32 s16, s9, s8
	s_ashr_i32 s8, s10, 3
	v_writelane_b32 v254, s8, 13
	s_lshr_b32 s8, s10, 3
	s_bfe_i64 s[8:9], s[8:9], 0x100000
	s_ashr_i32 s17, s16, 31
	s_lshl_b64 s[12:13], s[8:9], 18
	s_lshl_b64 s[10:11], s[16:17], 18
	v_writelane_b32 v254, s12, 14
	v_rcp_iflag_f32_e32 v0, v0
	s_nop 0
	v_writelane_b32 v254, s13, 15
	s_add_u32 s12, s36, s10
	s_addc_u32 s13, s37, s11
	s_add_u32 s20, s12, 0x20000
	v_writelane_b32 v254, s12, 16
	s_addc_u32 s21, s13, 0
	s_add_u32 s10, s50, s10
	v_writelane_b32 v254, s13, 17
	v_writelane_b32 v254, s20, 18
	s_addc_u32 s11, s51, s11
	s_add_u32 s12, s10, 0x20000
	v_writelane_b32 v254, s21, 19
	v_writelane_b32 v254, s10, 20
	s_addc_u32 s13, s11, 0
	s_add_i32 s6, s14, s6
	v_writelane_b32 v254, s11, 21
	s_ashr_i32 s10, s6, 31
	s_lshr_b32 s10, s10, 25
	s_add_i32 s10, s6, s10
	s_and_b32 s11, s10, 0xff80
	s_sub_i32 s6, s6, s11
	s_bfe_i32 s11, s6, 0x80000
	s_bfe_u32 s11, s11, 0x3000c
	v_writelane_b32 v254, s12, 22
	s_add_i32 s11, s6, s11
	s_ashr_i32 s10, s10, 7
	v_writelane_b32 v254, s13, 23
	s_and_b32 s12, s11, 0xf8
	s_sub_i32 s6, s6, s12
	s_bfe_i32 s11, s11, 0x80000
	s_lshl_b32 s10, s10, 3
	s_sext_i32_i16 s11, s11
	s_sext_i32_i8 s6, s6
	s_add_i32 s12, s10, s6
	s_ashr_i32 s6, s11, 3
	v_writelane_b32 v254, s6, 24
	s_lshr_b32 s6, s11, 3
	s_bfe_i64 s[10:11], s[6:7], 0x100000
	s_lshl_b64 s[10:11], s[10:11], 19
	s_ashr_i32 s13, s12, 31
	v_writelane_b32 v254, s10, 25
	s_mov_b32 s6, s12
	v_mul_f32_e32 v0, 0x4f7ffffe, v0
	v_writelane_b32 v254, s11, 26
	s_lshl_b64 s[10:11], s[12:13], 19
	v_writelane_b32 v254, s6, 27
	s_add_u32 s10, s36, s10
	s_addc_u32 s11, s37, s11
	v_writelane_b32 v254, s7, 28
	s_add_u32 s12, s10, 0x40000
	v_writelane_b32 v254, s10, 29
	s_addc_u32 s13, s11, 0
	s_ashr_i32 s19, s18, 31
	v_writelane_b32 v254, s11, 30
	v_writelane_b32 v254, s12, 31
	s_bfe_i64 s[10:11], s[0:1], 0x100000
	s_lshl_b64 s[10:11], s[10:11], 19
	v_writelane_b32 v254, s13, 32
	v_writelane_b32 v254, s10, 33
	s_mov_b32 s0, s18
	v_cvt_u32_f32_e32 v0, v0
	v_writelane_b32 v254, s11, 34
	s_lshl_b64 s[10:11], s[18:19], 19
	v_writelane_b32 v254, s0, 35
	s_add_u32 s10, s30, s10
; __device__ __forceinline__ int opq(int v) { asm volatile("" : "+v"(v)); return v; }
; __device__ __forceinline__ unsigned xb_ld(unsigned* p)              { return __hip_atomic_load(p, __ATOMIC_RELAXED, __HIP_MEMORY_SCOPE_AGENT); }
; __device__ __forceinline__ unsigned xb_add(unsigned* p, unsigned v) { return __hip_atomic_fetch_add(p, v, __ATOMIC_RELAXED, __HIP_MEMORY_SCOPE_AGENT); }
; #define XB_SPIN(cond, bar) do { unsigned _sp = 0; while (cond) { __builtin_amdgcn_s_sleep(1); \
;     if ((++_sp & 255u) == 0u) { if (xb_ld(&(bar)[XB_TMO])) break; if (_sp > XB_SPIN_CAP) { atomicAdd(&(bar)[XB_TMO], 1u); break; } } } } while (0)
; __device__ __forceinline__ void xcd_barrier(const XcdBarrier& b) {
;     ...
;             xb_add(&bar[XB_XGEN(b.x)], 1u);
;             asm volatile("s_waitcnt vmcnt(0)" ::: "memory");
;         } else {
;             XB_SPIN(xb_ld(&bar[XB_XGEN(b.x)]) == gen, bar);
;             __builtin_amdgcn_fence(__ATOMIC_ACQUIRE, "agent");
;             asm volatile("s_waitcnt vmcnt(0)" ::: "memory");
;         }
;     }
;     __syncthreads();
; __global__ void __launch_bounds__(512, 2) mk_fwd(Args a) {
;     ...
;         { pg8::Gemm g{ssmy, Wl + W_GLU, NTOK_P, 512, 512}; pg8::StaticOrder S; S.init(NTOK_P, 512, G, bx); EpiGlu E{ssmy, ssmg, a.in[I_BGLU] + l * 512};
;           pg8::gemm_phase<EpiGlu, pg8::StaticOrder, true, true>(lds, g, S, E);
;           { pg8::Gemm g1{bufA, Wl + W_IN + (size_t)(INC - 256) * DM, NTOK_P, 256, DM}; pg8::StaticOrder S1; S1.init(NTOK_P, 256, G, (bx + G - 128) % G); EpiIn E1{Z, ss1, a.in[I_BG] + l * 2048, INC / 256 - 1};
;             pg8::gemm_phase<EpiIn, pg8::StaticOrder, true, true>(lds, g1, S1, E1); }
;           skinny_gemm<2>(lds, ssmy, Wl + W_GLU, 512, 512, E, 192); }
;         { int u0 = -1, un = 0, us = 1;
;           if (G == 256) { if (bx >= 192) { u0 = bx - 192; un = 2; us = 64; } else if (bx < 128) { u0 = 128 + bx; un = 1; } }
;           else { u0 = bx; un = (2 * DEC_B - bx + G - 1) / G; us = G; }
;           for (int k = 0; k < un; ++k) { const int u = u0 + k * us; attn_sample_unit(a, lds, l, u >> 1, u & 1, opq(threadIdx.x)); } }
	s_addc_u32 s11, s31, s11
	v_writelane_b32 v254, s1, 36
	s_add_u32 s12, s10, 0x40000
	v_writelane_b32 v254, s10, 37
	s_addc_u32 s13, s11, 0
	s_mov_b32 s0, s16
	v_writelane_b32 v254, s11, 38
	v_writelane_b32 v254, s12, 39
	s_lshl_b64 s[10:11], s[16:17], 19
	v_readfirstlane_b32 s6, v0
	v_writelane_b32 v254, s13, 40
	s_lshl_b64 s[12:13], s[8:9], 19
	v_writelane_b32 v254, s12, 41
	s_add_u32 s10, s68, s10
	s_addc_u32 s11, s69, s11
	v_writelane_b32 v254, s13, 42
	s_add_u32 s12, s10, 0x40000
	v_writelane_b32 v254, s10, 43
	s_addc_u32 s13, s11, 0
	s_lshl_b64 s[8:9], s[8:9], 21
	v_writelane_b32 v254, s11, 44
	v_writelane_b32 v254, s12, 45
	s_mov_b64 s[20:21], 0x80
	s_nop 0
	v_writelane_b32 v254, s13, 46
	v_writelane_b32 v254, s8, 47
	s_nop 1
	v_writelane_b32 v254, s9, 48
	s_lshl_b64 s[8:9], s[16:17], 21
	s_add_u32 s8, s48, s8
	v_writelane_b32 v254, s0, 49
	s_addc_u32 s9, s49, s9
	s_add_u32 s10, s8, 0x100000
	v_writelane_b32 v254, s1, 50
	v_writelane_b32 v254, s8, 51
	s_addc_u32 s11, s9, 0
	s_sub_i32 s0, 0, s34
	s_mul_i32 s0, s0, s6
	s_mul_hi_u32 s0, s6, s0
	s_add_i32 s6, s6, s0
	s_mul_hi_u32 s0, s1, s6
	s_mul_i32 s0, s0, s34
	s_sub_i32 s0, s1, s0
	v_writelane_b32 v254, s9, 52
	s_sub_i32 s8, s0, s34
	s_cmp_ge_u32 s0, s34
	s_cselect_b32 s0, s8, s0
	s_sub_i32 s8, s0, s34
	v_writelane_b32 v254, s10, 53
	s_cmp_ge_u32 s0, s34
	s_nop 0
	v_writelane_b32 v254, s11, 54
	s_cselect_b32 s11, s8, s0
	s_cmpk_lt_i32 s11, 0x1a0
	s_cselect_b64 s[8:9], -1, 0
	s_abs_i32 s0, s34
	v_cvt_f32_u32_e32 v0, s0
	v_writelane_b32 v254, s8, 55
	v_rcp_iflag_f32_e32 v0, v0
	s_nop 0
	v_writelane_b32 v254, s9, 56
	s_sub_i32 s8, 0, s0
	v_mul_f32_e32 v0, 0x4f7ffffe, v0
	v_cvt_u32_f32_e32 v0, v0
	s_nop 0
	v_readfirstlane_b32 s9, v0
	s_mul_i32 s8, s8, s9
	s_mul_hi_u32 s8, s9, s8
	s_add_i32 s9, s9, s8
	s_abs_i32 s8, s7
	s_mul_hi_u32 s10, s8, s9
	s_mul_i32 s10, s10, s0
	s_sub_i32 s8, s8, s10
	s_ashr_i32 s7, s7, 31
	s_sub_i32 s10, s8, s0
	s_cmp_ge_u32 s8, s0
	s_cselect_b32 s8, s10, s8
	s_sub_i32 s10, s8, s0
	s_cmp_ge_u32 s8, s0
	s_cselect_b32 s8, s10, s8
	s_xor_b32 s8, s8, s7
	s_sub_i32 s8, s8, s7
	s_cmp_lt_i32 s8, 64
	s_cselect_b64 s[12:13], -1, 0
	v_writelane_b32 v254, s12, 57
	s_ashr_i32 s7, s8, 31
	v_mov_b32_e32 v0, v1
	v_writelane_b32 v254, s13, 58
	v_writelane_b32 v254, s7, 59
	s_lshr_b32 s7, s7, 29
	s_add_i32 s7, s8, s7
	s_ashr_i32 s10, s7, 3
	v_writelane_b32 v254, s10, 60
	s_and_b32 s7, s7, -8
	v_writelane_b32 v254, s8, 61
	s_sub_i32 s7, s8, s7
	s_mul_hi_u32 s8, s9, 0xc0
	s_cmp_gt_i32 s7, -1
	s_mul_i32 s8, s8, s0
	s_cselect_b64 s[12:13], -1, 0
	s_sub_i32 s8, 0xc0, s8
	s_lshl_b32 s10, s7, 3
	v_writelane_b32 v255, s10, 0
	s_sub_i32 s10, s8, s0
	s_cmp_ge_u32 s8, s0
	s_cselect_b32 s8, s10, s8
	s_sub_i32 s10, s8, s0
	s_cmp_ge_u32 s8, s0
	s_cselect_b32 s8, s10, s8
	s_sub_i32 s1, s1, s8
	s_mul_hi_u32 s6, s1, s6
	s_mul_i32 s6, s6, s34
	s_sub_i32 s1, s1, s6
	s_sub_i32 s6, s1, s34
	s_cmp_ge_u32 s1, s34
	s_cselect_b32 s1, s6, s1
	s_sub_i32 s6, s1, s34
	s_cmp_ge_u32 s1, s34
	s_cselect_b32 s10, s6, s1
	v_writelane_b32 v254, s12, 62
	s_cmpk_lt_i32 s10, 0x80
	v_mov_b64_e32 v[18:19], v[6:7]
	v_writelane_b32 v254, s13, 63
	s_cselect_b64 s[12:13], -1, 0
	s_sub_i32 s1, 0xffffff01, s5
	s_max_i32 s1, s4, s1
	s_mul_hi_u32 s5, s1, s9
	s_mul_i32 s6, s5, s0
	s_sub_i32 s1, s1, s6
	s_xor_b32 s4, s4, s34
	s_ashr_i32 s4, s4, 31
	s_add_i32 s6, s5, 1
	s_sub_i32 s8, s1, s0
	s_cmp_ge_u32 s1, s0
	s_cselect_b32 s5, s6, s5
	s_cselect_b32 s1, s8, s1
	s_add_i32 s6, s5, 1
	v_writelane_b32 v255, s12, 1
	s_cmp_ge_u32 s1, s0
	s_mul_i32 s0, s35, s34
	v_writelane_b32 v255, s13, 2
	s_mul_i32 s0, s0, s58
	v_writelane_b32 v255, s0, 3
	s_cselect_b32 s0, s6, s5
	s_xor_b32 s0, s0, s4
	s_sub_i32 s0, s0, s4
	v_writelane_b32 v255, s0, 4
	s_mul_i32 s0, s7, 9
	s_cmpk_lt_i32 s11, 0x100
	v_writelane_b32 v255, s0, 5
	s_cselect_b64 s[0:1], -1, 0
	v_writelane_b32 v255, s0, 6
	s_cmpk_lt_i32 s11, 0x200
	v_mov_b64_e32 v[16:17], v[4:5]
	v_writelane_b32 v255, s1, 7
	s_cselect_b64 s[0:1], -1, 0
	v_writelane_b32 v255, s0, 8
	s_lshl_b32 s82, s34, 6
	v_mov_b64_e32 v[14:15], v[2:3]
	v_writelane_b32 v255, s1, 9
	s_lshl_b32 s0, s94, 5
	s_add_i32 s78, s0, 0
	s_lshl_b32 s0, s11, 3
	v_writelane_b32 v255, s0, 10
	s_lshl_b32 s0, s11, 6
	v_writelane_b32 v255, s0, 11
	s_add_u32 s0, s70, 0x6a80800
	v_writelane_b32 v255, s0, 12
	s_addc_u32 s0, s71, 0
	v_writelane_b32 v255, s0, 13
	s_lshl_b32 s0, s10, 2
	v_writelane_b32 v255, s0, 14
	v_writelane_b32 v255, s10, 15
	s_lshl_b32 s0, s10, 6
	v_writelane_b32 v255, s0, 16
	v_writelane_b32 v255, s11, 17
	s_lshl_b32 s0, s11, 2
	v_writelane_b32 v255, s0, 18
	s_add_i32 s0, 0, 0x23fc0
	v_writelane_b32 v255, s0, 19
	s_add_i32 s0, 0, 0x23fc4
	v_writelane_b32 v255, s0, 20
	s_add_i32 s0, 0, 0x11810
	v_writelane_b32 v255, s0, 21
	s_add_i32 s0, 0, 0x9000
	v_writelane_b32 v255, s0, 22
	v_cmp_eq_u32_e64 s[0:1], 0, v20
	v_mov_b64_e32 v[12:13], v[0:1]
	v_mov_b64_e32 v[10:11], v[6:7]
	v_writelane_b32 v255, s0, 23
	v_mov_b64_e32 v[8:9], v[4:5]
	v_mov_b64_e32 v[6:7], v[2:3]
	v_writelane_b32 v255, s1, 24
	s_mov_b64 s[0:1], -1
	v_writelane_b32 v255, s0, 25
	v_mov_b64_e32 v[4:5], v[0:1]
	s_lshl_b32 s83, s34, 2
	v_writelane_b32 v255, s1, 26
	v_writelane_b32 v255, s96, 27
	s_mov_b32 s35, 0x18000
	s_nop 0
	v_writelane_b32 v255, s97, 28
	v_writelane_b32 v255, s94, 29
	v_writelane_b32 v255, s28, 30
	s_nop 1
	v_writelane_b32 v255, s29, 31
	v_writelane_b32 v255, s95, 32
	v_writelane_b32 v255, s46, 33
	s_nop 1
	v_writelane_b32 v255, s47, 34
	s_branch .LBB0_209
.LBB0_206:
	s_or_b64 exec, exec, s[8:9]
.LBB0_207:
	s_or_b64 exec, exec, s[0:1]
	s_mov_b64 s[0:1], 0
	s_waitcnt lgkmcnt(0)
	s_barrier

; #define LAS __attribute__((address_space(3)))
; __device__ __forceinline__ unsigned xb_ld(unsigned* p)              { return __hip_atomic_load(p, __ATOMIC_RELAXED, __HIP_MEMORY_SCOPE_AGENT); }
; __device__ __forceinline__ unsigned xb_add(unsigned* p, unsigned v) { return __hip_atomic_fetch_add(p, v, __ATOMIC_RELAXED, __HIP_MEMORY_SCOPE_AGENT); }
; #define XB_SPIN(cond, bar) do { unsigned _sp = 0; while (cond) { __builtin_amdgcn_s_sleep(1); \
;     if ((++_sp & 255u) == 0u) { if (xb_ld(&(bar)[XB_TMO])) break; if (_sp > XB_SPIN_CAP) { atomicAdd(&(bar)[XB_TMO], 1u); break; } } } } while (0)
; __device__ __forceinline__ void attn_prompt_unit(const Args& a, LAS unsigned char* lds, int l, int b, int qb, int kvh, int tid) {
;     constexpr int KST = 72, VST = 272;
;     LAS bf16_t* Ks = (LAS bf16_t*)lds; LAS bf16_t* Vt = Ks + 256 * KST; LAS float* kmaxs = (LAS float*)(Vt + 64 * VST);
;     const bf16_t* Z = (const bf16_t*)(a.ws + WS_C);
;     const float* gk = a.in[I_KG] + l * 64; const float* gq = a.in[I_QG] + l * 64;
;     const int wave = tid >> 6, lane = tid & 63, r = lane & 15, qd = lane >> 4, g = wave >> 1, qh = wave & 1, h = kvh * 4 + g;
; __device__ __forceinline__ void xcd_barrier(const XcdBarrier& b) {
;     ...
;             xb_add(&bar[XB_XGEN(b.x)], 1u);
;             asm volatile("s_waitcnt vmcnt(0)" ::: "memory");
;         } else {
;             XB_SPIN(xb_ld(&bar[XB_XGEN(b.x)]) == gen, bar);
;             __builtin_amdgcn_fence(__ATOMIC_ACQUIRE, "agent");
;             asm volatile("s_waitcnt vmcnt(0)" ::: "memory");
;         }
;     }
;     __syncthreads();
.LBB0_327:
	s_or_b64 exec, exec, s[8:9]
.LBB0_328:
	s_or_b64 exec, exec, s[0:1]
	s_lshl_b32 s26, s42, 6
	v_readlane_b32 s4, v252, 38
	s_lshl_b64 s[0:1], s[26:27], 2
	v_readlane_b32 s8, v252, 42
	v_readlane_b32 s9, v252, 43
	s_mov_b32 s4, s42
	s_add_u32 s42, s8, s0
	v_readlane_b32 s6, v252, 40
	s_addc_u32 s43, s9, s1
	v_readlane_b32 s7, v252, 41
	s_add_u32 s44, s6, s0
	s_addc_u32 s45, s7, s1
	v_readlane_b32 s0, v253, 30
	v_readlane_b32 s1, v253, 31
	v_readlane_b32 s5, v252, 39
	v_readlane_b32 s14, v252, 48
	v_cndmask_b32_e64 v0, 0, 1, s[0:1]
	s_mov_b32 s14, s4
	s_lshl_b32 s93, s4, 3
	v_cmp_ne_u32_e64 s[4:5], 1, v0
	v_readlane_b32 s10, v252, 44
	s_andn2_b64 vcc, exec, s[0:1]
	v_writelane_b32 v255, s4, 39
	s_mov_b32 s10, s2
	s_waitcnt lgkmcnt(0)
	v_writelane_b32 v255, s5, 40
	s_barrier
	v_readlane_b32 s11, v252, 45
	v_readlane_b32 s12, v252, 46
	v_readlane_b32 s13, v252, 47
	v_readlane_b32 s15, v252, 49
	v_readlane_b32 s16, v252, 50
	v_readlane_b32 s17, v252, 51
	v_readlane_b32 s18, v252, 52
	v_readlane_b32 s19, v252, 53
	s_cbranch_vccz .LBB0_364

; __device__ __forceinline__ int opq(int v) { asm volatile("" : "+v"(v)); return v; }
; __device__ __forceinline__ unsigned xb_ld(unsigned* p)              { return __hip_atomic_load(p, __ATOMIC_RELAXED, __HIP_MEMORY_SCOPE_AGENT); }
; __device__ __forceinline__ unsigned xb_add(unsigned* p, unsigned v) { return __hip_atomic_fetch_add(p, v, __ATOMIC_RELAXED, __HIP_MEMORY_SCOPE_AGENT); }
; #define XB_SPIN(cond, bar) do { unsigned _sp = 0; while (cond) { __builtin_amdgcn_s_sleep(1); \
;     if ((++_sp & 255u) == 0u) { if (xb_ld(&(bar)[XB_TMO])) break; if (_sp > XB_SPIN_CAP) { atomicAdd(&(bar)[XB_TMO], 1u); break; } } } } while (0)
; template <bool PASS_B> __device__ __forceinline__ void ssm_tables(const Args& a, int l, int gq, int wave, SsmTab& T) {
;     const int lane = opq(threadIdx.x) & 63, r = lane & 15, qd = lane >> 4, g = gq * 8 + wave;
;     T.ta = ((const f32x4*)(a.ws + WS_TA))[(l * NG + g) * NP + lane];
;     const bf16_t* tbh = (const bf16_t*)(a.ws + WS_TB) + (size_t)(l * NG + g) * 128 * GC + r * GC + 8 * (qd & 1);
; #pragma unroll
;     for (int pt = 0; pt < 8; ++pt) { const bf16x8 v = *(const bf16x8*)(tbh + pt * 16 * GC); T.af[pt] = qd < 2 ? v : (bf16x8){0, 0, 0, 0, 0, 0, 0, 0}; }
; __device__ __forceinline__ void xcd_barrier(const XcdBarrier& b) {
;     ...
;             xb_add(&bar[XB_XGEN(b.x)], 1u);
;             asm volatile("s_waitcnt vmcnt(0)" ::: "memory");
;         } else {
;             XB_SPIN(xb_ld(&bar[XB_XGEN(b.x)]) == gen, bar);
;             __builtin_amdgcn_fence(__ATOMIC_ACQUIRE, "agent");
;             asm volatile("s_waitcnt vmcnt(0)" ::: "memory");
;         }
;     }
;     __syncthreads();
.LBB0_428:
	s_or_b64 exec, exec, s[14:15]
.LBB0_429:
	s_or_b64 exec, exec, s[0:1]
	v_mov_b32_e32 v21, v184
	s_waitcnt lgkmcnt(0)
	s_barrier
	v_readlane_b32 s0, v253, 36
	v_and_b32_e32 v22, 63, v21
	v_or_b32_e32 v0, s62, v22
	v_readlane_b32 s1, v253, 37
	v_and_b32_e32 v20, 15, v21
	v_mov_b32_e32 v28, 0
	v_lshl_add_u64 v[2:3], v[0:1], 4, s[0:1]
	global_load_dwordx4 v[76:79], v[2:3], off
	v_lshlrev_b32_e32 v0, 5, v20
	v_lshl_add_u64 v[2:3], s[8:9], 0, v[0:1]
	v_and_b32_e32 v0, 16, v21
	v_lshl_add_u64 v[2:3], v[2:3], 0, v[0:1]
	v_cmp_gt_u32_e32 vcc, 32, v22
	s_waitcnt vmcnt(2)
	v_mov_b32_e32 v32, 0
	v_mov_b32_e32 v33, v28
	v_mov_b32_e32 v34, v28
	v_mov_b32_e32 v35, v28
	v_mov_b32_e32 v36, 0
	v_mov_b32_e32 v37, v28
	s_waitcnt vmcnt(1)
	v_mov_b32_e32 v38, v28
	v_mov_b32_e32 v39, v28
	s_and_saveexec_b64 s[0:1], vcc
	s_cbranch_execz .LBB0_431
	global_load_dwordx4 v[32:35], v[2:3], off
	global_load_dwordx4 v[36:39], v[2:3], off offset:512

; #define PG8_STAGE(bufoff, gbase, voff) do { _Pragma("unroll") for (int _i = 0; _i < 2; ++_i) \
;         __builtin_amdgcn_global_load_lds((const unsigned*)((const char*)(gbase) + (voff)[_i]), (PG8_LAS unsigned*)(lds + (bufoff) + ldsw + _i * 8192), 16, 0, 0); } while (0)
; #define PG8_WAIT_V(n) asm volatile("s_waitcnt vmcnt(" #n ")" ::: "memory")
; #define PG8_BAR __builtin_amdgcn_s_barrier()
; template <class Epi, class Sched, bool ALIGN_EPI = false, bool SP2 = false>
; __device__ __forceinline__ void gemm_phase(PG8_LAS unsigned char* lds, const Gemm g, const Sched& S, const Epi& E) {
;     ...
;     for (int i = 0; i < 2; ++i) { int R, C; stage_rc(tid * 16 + i * 8192, R, C); const int Rb = Epi::PERM ? ((R & ~31) + perm32(R & 31)) : R;
;         voffA[i] = (unsigned)(R * K + C) * 2u; voffB[i] = (unsigned)(Rb * K + C) * 2u; }
;     const size_t kstep = (size_t)(BK * 2);
;     const size_t hstep = (size_t)HALF * K * 2;
;     const size_t tstep = 2 * hstep;
;     const unsigned ldsw = (unsigned)wid * 1024u;
;     const int aoff = lds_byte(wr * 64 + fr, fq * 8), boff = lds_byte(wc * 32 + fr, fq * 8);
;     ...
;     Unit cur, nxt; int ui = 0;
;     if (!S.next(0, cur)) return;
;     f32x4 acc[2][2][4][2];
; #pragma unroll
;     for (int a = 0; a < 2; ++a)
; #pragma unroll
;         for (int b = 0; b < 2; ++b)
; #pragma unroll
;             for (int m = 0; m < 4; ++m)
; #pragma unroll
;                 for (int n = 0; n < 2; ++n) acc[a][b][m][n] = (f32x4){0.f, 0.f, 0.f, 0.f};
;     bf16x8 At[4][2], B0[2][2], B1[2][2];
;     const char* cA = (const char*)g.A + (size_t)cur.pm * tstep; const char* cB = (const char*)g.Bt + (size_t)cur.pn * tstep;
;     S.a_ready(cur);
;     if constexpr (SP2) {
;         PG8_STAGE(PG8_SB(0, 0), cB, voffB); PG8_STAGE(PG8_SB(0, 1), cB + hstep, voffB); PG8_STAGE(PG8_SA(0, 0), cA, voffA); PG8_STAGE(PG8_SA(0, 1), cA + hstep, voffA);
;         if (wr == 1) PG8_BAR;
;         PG8_WAIT_V(2); PG8_BAR;
.LBB0_545:
	s_or_b64 exec, exec, s[10:11]
.LBB0_546:
	s_or_b64 exec, exec, s[0:1]
	v_readlane_b32 s0, v255, 37
	v_readlane_b32 s4, v252, 16
	s_add_u32 s26, s0, 0x680000
	v_readlane_b32 s0, v255, 38
	s_mov_b32 s25, s27
	v_readlane_b32 s10, v252, 22
	v_readlane_b32 s11, v252, 23
	v_readlane_b32 s14, v252, 26
	v_readlane_b32 s15, v252, 27
	s_addc_u32 s74, s0, 0
	s_lshl_b64 s[0:1], s[24:25], 2
	v_readlane_b32 s8, v252, 20
	s_mov_b64 s[10:11], s[14:15]
	v_readlane_b32 s9, v252, 21
	s_add_u32 s8, s10, s0
	s_addc_u32 s9, s11, s1
	v_readlane_b32 s0, v253, 52
	v_readlane_b32 s6, v252, 18
	v_mov_b32_e32 v20, v184
	v_readlane_b32 s1, v253, 53
	s_waitcnt lgkmcnt(0)
	s_barrier
	s_and_b64 vcc, s[0:1], exec
	v_readfirstlane_b32 s6, v20
	v_readlane_b32 s5, v252, 17
	v_readlane_b32 s7, v252, 19
	v_readlane_b32 s12, v252, 24
	v_readlane_b32 s13, v252, 25
	v_readlane_b32 s16, v252, 28
	v_readlane_b32 s17, v252, 29
	v_readlane_b32 s18, v252, 30
	v_readlane_b32 s19, v252, 31
	s_cbranch_vccz .LBB0_566
	v_lshlrev_b32_e32 v0, 4, v20
	v_add_u32_e32 v2, 0x2000, v0
	v_ashrrev_i32_e32 v3, 31, v2
	v_lshrrev_b32_e32 v3, 22, v3
	v_add_u32_e32 v3, v2, v3
	v_ashrrev_i32_e32 v21, 10, v3
	v_mul_i32_i24_e32 v3, 0x400, v21
	v_sub_u32_e32 v2, v2, v3
	v_lshrrev_b32_e32 v3, 4, v2
	v_bitop3_b32 v2, v3, v2, 32 bitop3:0x6c
	v_ashrrev_i32_e32 v3, 31, v2
	v_lshrrev_b32_e32 v3, 26, v3
	v_add_u32_e32 v3, v2, v3
	v_lshlrev_b32_e32 v23, 3, v21
	v_ashrrev_i32_e32 v22, 6, v3
	v_and_b32_e32 v23, -16, v23
	v_add_u32_e32 v24, v22, v23
	v_and_b32_e32 v23, 3, v22
	s_mov_b32 s0, 0x3fffe0
	v_lshrrev_b32_e32 v25, 2, v24
	v_lshlrev_b32_e32 v26, 1, v24
	v_and_b32_e32 v3, 0xc0, v3
	v_and_or_b32 v23, v24, s0, v23
	v_and_b32_e32 v25, 4, v25
	v_and_b32_e32 v26, 24, v26
	v_sub_u32_e32 v2, v2, v3
	v_mov_b32_e32 v30, 1
	v_or3_b32 v25, v23, v25, v26
	v_lshlrev_b32_e32 v23, 5, v21
	v_ashrrev_i16_sdwa v2, v30, sext(v2) dst_sel:DWORD dst_unused:UNUSED_PAD src0_sel:DWORD src1_sel:BYTE_0
	v_and_b32_e32 v26, 32, v23
	v_bfe_i32 v23, v2, 0, 16
	v_add_lshl_u32 v3, v26, v23, 1
	v_lshl_add_u32 v2, v25, 10, v3
	v_lshl_add_u32 v190, v24, 10, v3
	v_bfe_i32 v3, v20, 27, 1
	v_lshrrev_b32_e32 v3, 22, v3
	v_add_u32_e32 v3, v0, v3
	v_and_b32_e32 v3, 0xfffffc00, v3
	v_sub_u32_e32 v0, v0, v3
	v_lshrrev_b32_e32 v3, 4, v0
	v_ashrrev_i32_e32 v25, 31, v20
	v_bitop3_b32 v0, v3, v0, 32 bitop3:0x6c
	v_lshrrev_b32_e32 v25, 26, v25
	v_ashrrev_i32_e32 v3, 31, v0
	v_add_u32_e32 v25, v20, v25
	v_lshrrev_b32_e32 v3, 26, v3
	v_ashrrev_i32_e32 v25, 6, v25
	v_add_u32_e32 v3, v0, v3
	v_lshlrev_b32_e32 v26, 3, v25
	v_ashrrev_i32_e32 v24, 6, v3
	v_and_b32_e32 v26, -16, v26
	v_add_u32_e32 v27, v24, v26
	v_and_b32_e32 v26, 3, v24
	v_lshrrev_b32_e32 v28, 2, v27
	v_lshlrev_b32_e32 v29, 1, v27
	v_and_b32_e32 v3, 0xc0, v3
	s_ashr_i32 s12, s6, 6
	v_and_or_b32 v26, v27, s0, v26
	v_and_b32_e32 v28, 4, v28
	v_and_b32_e32 v29, 24, v29
	v_sub_u32_e32 v0, v0, v3
	s_ashr_i32 s7, s6, 8
	s_lshl_b32 s72, s12, 10
	v_or3_b32 v28, v26, v28, v29
	v_lshlrev_b32_e32 v26, 5, v25
	v_ashrrev_i16_sdwa v0, v30, sext(v0) dst_sel:DWORD dst_unused:UNUSED_PAD src0_sel:DWORD src1_sel:BYTE_0
	v_readlane_b32 s0, v254, 1
	v_and_b32_e32 v29, 32, v26
	v_bfe_i32 v26, v0, 0, 16
	v_readlane_b32 s1, v254, 2
	s_add_u32 s0, s26, s0
	v_add_lshl_u32 v3, v29, v26, 1
	s_addc_u32 s1, s74, s1
	s_add_i32 s73, s72, 0
	v_lshl_add_u32 v0, v28, 10, v3
	s_add_i32 m0, s73, 0x10000
	v_readlane_b32 s4, v254, 6
	global_load_lds_dwordx4 v0, s[0:1]
	s_add_i32 m0, s73, 0x12000
	s_add_u32 s10, s0, 0x20000
	global_load_lds_dwordx4 v2, s[0:1]
	s_addc_u32 s11, s1, 0
	s_add_i32 m0, s73, 0x14000
	v_lshl_add_u32 v192, v27, 10, v3
	global_load_lds_dwordx4 v0, s[10:11]
	s_add_i32 m0, s73, 0x16000
	v_readlane_b32 s5, v254, 7
	global_load_lds_dwordx4 v2, s[10:11]
	s_mov_b32 m0, s73
	s_add_i32 s75, s73, 0x2000
	s_add_i32 s94, s73, 0x4000
	s_nop 0
	global_load_lds_dwordx4 v192, s[4:5]
	s_mov_b32 m0, s75
	s_add_i32 s95, s73, 0x6000
	global_load_lds_dwordx4 v190, s[4:5]
	v_readlane_b32 s4, v254, 8
	s_mov_b32 m0, s94
	v_readlane_b32 s5, v254, 9
	s_cmp_eq_u32 s7, 1
	s_cselect_b64 s[10:11], -1, 0
	s_cmp_lg_u32 s7, 1
	s_nop 1
	global_load_lds_dwordx4 v192, s[4:5]
	s_mov_b32 m0, s95
	s_nop 0
	global_load_lds_dwordx4 v190, s[4:5]
	s_cbranch_scc1 .LBB0_549
	s_barrier

; #define PG8_STAGE(bufoff, gbase, voff) do { _Pragma("unroll") for (int _i = 0; _i < 2; ++_i) \
;         __builtin_amdgcn_global_load_lds((const unsigned*)((const char*)(gbase) + (voff)[_i]), (PG8_LAS unsigned*)(lds + (bufoff) + ldsw + _i * 8192), 16, 0, 0); } while (0)
; #define PG8_WAIT_V(n) asm volatile("s_waitcnt vmcnt(" #n ")" ::: "memory")
; #define PG8_BAR __builtin_amdgcn_s_barrier()
; template <class Epi, class Sched, bool ALIGN_EPI = false, bool SP2 = false>
; __device__ __forceinline__ void gemm_phase(PG8_LAS unsigned char* lds, const Gemm g, const Sched& S, const Epi& E) {
;     ...
;     for (int i = 0; i < 2; ++i) { int R, C; stage_rc(tid * 16 + i * 8192, R, C); const int Rb = Epi::PERM ? ((R & ~31) + perm32(R & 31)) : R;
;         voffA[i] = (unsigned)(R * K + C) * 2u; voffB[i] = (unsigned)(Rb * K + C) * 2u; }
;     const size_t kstep = (size_t)(BK * 2);
;     const size_t hstep = (size_t)HALF * K * 2;
;     const size_t tstep = 2 * hstep;
;     const unsigned ldsw = (unsigned)wid * 1024u;
;     const int aoff = lds_byte(wr * 64 + fr, fq * 8), boff = lds_byte(wc * 32 + fr, fq * 8);
;     ...
;     Unit cur, nxt; int ui = 0;
;     if (!S.next(0, cur)) return;
;     f32x4 acc[2][2][4][2];
; #pragma unroll
;     for (int a = 0; a < 2; ++a)
; #pragma unroll
;         for (int b = 0; b < 2; ++b)
; #pragma unroll
;             for (int m = 0; m < 4; ++m)
; #pragma unroll
;                 for (int n = 0; n < 2; ++n) acc[a][b][m][n] = (f32x4){0.f, 0.f, 0.f, 0.f};
;     bf16x8 At[4][2], B0[2][2], B1[2][2];
;     const char* cA = (const char*)g.A + (size_t)cur.pm * tstep; const char* cB = (const char*)g.Bt + (size_t)cur.pn * tstep;
;     S.a_ready(cur);
;     if constexpr (SP2) {
;         PG8_STAGE(PG8_SB(0, 0), cB, voffB); PG8_STAGE(PG8_SB(0, 1), cB + hstep, voffB); PG8_STAGE(PG8_SA(0, 0), cA, voffA); PG8_STAGE(PG8_SA(0, 1), cA + hstep, voffA);
;         if (wr == 1) PG8_BAR;
;         PG8_WAIT_V(2); PG8_BAR;
.LBB0_662:
	s_or_b64 exec, exec, s[8:9]
.LBB0_663:
	s_or_b64 exec, exec, s[0:1]
	v_readlane_b32 s0, v255, 37
	s_add_u32 s26, s0, 0x700000
	v_readlane_b32 s0, v255, 38
	s_addc_u32 s54, s0, 0
	v_readlane_b32 s0, v255, 39
	v_mov_b32_e32 v21, v184
	v_readlane_b32 s1, v255, 40
	s_waitcnt lgkmcnt(0)
	s_barrier
	s_and_b64 vcc, exec, s[0:1]
	v_readfirstlane_b32 s6, v21
	s_cbranch_vccnz .LBB0_683
	v_lshlrev_b32_e32 v0, 4, v21
	v_add_u32_e32 v2, 0x2000, v0
	v_ashrrev_i32_e32 v3, 31, v2
	v_lshrrev_b32_e32 v3, 22, v3
	v_add_u32_e32 v3, v2, v3
	v_ashrrev_i32_e32 v20, 10, v3
	v_mul_i32_i24_e32 v3, 0x400, v20
	v_sub_u32_e32 v2, v2, v3
	v_lshrrev_b32_e32 v3, 4, v2
	v_bitop3_b32 v2, v3, v2, 32 bitop3:0x6c
	v_ashrrev_i32_e32 v3, 31, v2
	v_lshrrev_b32_e32 v3, 26, v3
	v_add_u32_e32 v3, v2, v3
	v_lshlrev_b32_e32 v23, 3, v20
	v_ashrrev_i32_e32 v22, 6, v3
	v_and_b32_e32 v23, -16, v23
	v_add_u32_e32 v24, v22, v23
	v_and_b32_e32 v23, 3, v22
	s_mov_b32 s0, 0x3fffe0
	v_lshrrev_b32_e32 v25, 2, v24
	v_lshlrev_b32_e32 v26, 1, v24
	v_and_b32_e32 v3, 0xc0, v3
	v_and_or_b32 v23, v24, s0, v23
	v_and_b32_e32 v25, 4, v25
	v_and_b32_e32 v26, 24, v26
	v_sub_u32_e32 v2, v2, v3
	v_mov_b32_e32 v30, 1
	v_or3_b32 v25, v23, v25, v26
	v_lshlrev_b32_e32 v23, 5, v20
	v_ashrrev_i16_sdwa v2, v30, sext(v2) dst_sel:DWORD dst_unused:UNUSED_PAD src0_sel:DWORD src1_sel:BYTE_0
	v_and_b32_e32 v26, 32, v23
	v_bfe_i32 v23, v2, 0, 16
	v_add_lshl_u32 v3, v26, v23, 1
	v_lshl_add_u32 v2, v25, 10, v3
	v_lshl_add_u32 v148, v24, 10, v3
	v_bfe_i32 v3, v21, 27, 1
	v_lshrrev_b32_e32 v3, 22, v3
	v_add_u32_e32 v3, v0, v3
	v_and_b32_e32 v3, 0xfffffc00, v3
	v_sub_u32_e32 v0, v0, v3
	v_lshrrev_b32_e32 v3, 4, v0
	v_ashrrev_i32_e32 v25, 31, v21
	v_bitop3_b32 v0, v3, v0, 32 bitop3:0x6c
	v_lshrrev_b32_e32 v25, 26, v25
	v_ashrrev_i32_e32 v3, 31, v0
	v_add_u32_e32 v25, v21, v25
	v_lshrrev_b32_e32 v3, 26, v3
	v_ashrrev_i32_e32 v25, 6, v25
	v_add_u32_e32 v3, v0, v3
	v_lshlrev_b32_e32 v26, 3, v25
	v_ashrrev_i32_e32 v24, 6, v3
	v_and_b32_e32 v26, -16, v26
	v_add_u32_e32 v27, v24, v26
	v_and_b32_e32 v26, 3, v24
	v_lshrrev_b32_e32 v28, 2, v27
	v_lshlrev_b32_e32 v29, 1, v27
	v_and_b32_e32 v3, 0xc0, v3
	s_ashr_i32 s8, s6, 6
	v_and_or_b32 v26, v27, s0, v26
	v_and_b32_e32 v28, 4, v28
	v_and_b32_e32 v29, 24, v29
	v_sub_u32_e32 v0, v0, v3
	s_ashr_i32 s7, s6, 8
	s_lshl_b32 s55, s8, 10
	v_or3_b32 v28, v26, v28, v29
	v_lshlrev_b32_e32 v26, 5, v25
	v_ashrrev_i16_sdwa v0, v30, sext(v0) dst_sel:DWORD dst_unused:UNUSED_PAD src0_sel:DWORD src1_sel:BYTE_0
	v_readlane_b32 s0, v254, 14
	v_and_b32_e32 v29, 32, v26
	v_bfe_i32 v26, v0, 0, 16
	v_readlane_b32 s1, v254, 15
	s_add_u32 s0, s26, s0
	v_add_lshl_u32 v3, v29, v26, 1
	s_addc_u32 s1, s54, s1
	s_add_i32 s56, s55, 0
	v_lshl_add_u32 v0, v28, 10, v3
	s_add_i32 m0, s56, 0x10000
	v_lshl_add_u32 v150, v27, 10, v3
	global_load_lds_dwordx4 v0, s[0:1]
	s_add_i32 m0, s56, 0x12000
	s_add_u32 s4, s0, 0x20000
	global_load_lds_dwordx4 v2, s[0:1]
	s_addc_u32 s5, s1, 0
	s_add_i32 m0, s56, 0x14000
	s_add_i32 s57, s56, 0x2000
	global_load_lds_dwordx4 v0, s[4:5]
	s_add_i32 m0, s56, 0x16000
	s_add_i32 s58, s56, 0x4000
	global_load_lds_dwordx4 v2, s[4:5]
	v_readlane_b32 s4, v254, 16
	s_mov_b32 m0, s56
	v_readlane_b32 s5, v254, 17
	s_add_i32 s59, s56, 0x6000
	s_cmp_eq_u32 s7, 1
	s_nop 2
	global_load_lds_dwordx4 v150, s[4:5]
	s_mov_b32 m0, s57
	s_nop 0
	global_load_lds_dwordx4 v148, s[4:5]
	v_readlane_b32 s4, v254, 18
	s_mov_b32 m0, s58
	v_readlane_b32 s5, v254, 19
	s_nop 4
	global_load_lds_dwordx4 v150, s[4:5]
	s_mov_b32 m0, s59
	s_nop 0
	global_load_lds_dwordx4 v148, s[4:5]
	s_cselect_b64 s[4:5], -1, 0
	s_cmp_lg_u32 s7, 1
	s_cbranch_scc1 .LBB0_666
	s_barrier

; #define PG8_STAGE(bufoff, gbase, voff) do { _Pragma("unroll") for (int _i = 0; _i < 2; ++_i) \
;         __builtin_amdgcn_global_load_lds((const unsigned*)((const char*)(gbase) + (voff)[_i]), (PG8_LAS unsigned*)(lds + (bufoff) + ldsw + _i * 8192), 16, 0, 0); } while (0)
; #define PG8_BAR __builtin_amdgcn_s_barrier()
; __device__ __forceinline__ unsigned xb_ld(unsigned* p)              { return __hip_atomic_load(p, __ATOMIC_RELAXED, __HIP_MEMORY_SCOPE_AGENT); }
; template <class Epi, class Sched, bool ALIGN_EPI = false, bool SP2 = false>
; __device__ __forceinline__ void gemm_phase(PG8_LAS unsigned char* lds, const Gemm g, const Sched& S, const Epi& E) {
;     ...
;     for (int i = 0; i < 2; ++i) { int R, C; stage_rc(tid * 16 + i * 8192, R, C); const int Rb = Epi::PERM ? ((R & ~31) + perm32(R & 31)) : R;
;         voffA[i] = (unsigned)(R * K + C) * 2u; voffB[i] = (unsigned)(Rb * K + C) * 2u; }
;     const size_t kstep = (size_t)(BK * 2);
;     const size_t hstep = (size_t)HALF * K * 2;
;     const size_t tstep = 2 * hstep;
;     const unsigned ldsw = (unsigned)wid * 1024u;
;     const int aoff = lds_byte(wr * 64 + fr, fq * 8), boff = lds_byte(wc * 32 + fr, fq * 8);
;     ...
;     Unit cur, nxt; int ui = 0;
;     if (!S.next(0, cur)) return;
;     f32x4 acc[2][2][4][2];
; #pragma unroll
;     for (int a = 0; a < 2; ++a)
; #pragma unroll
;         for (int b = 0; b < 2; ++b)
; #pragma unroll
;             for (int m = 0; m < 4; ++m)
; #pragma unroll
;                 for (int n = 0; n < 2; ++n) acc[a][b][m][n] = (f32x4){0.f, 0.f, 0.f, 0.f};
;     bf16x8 At[4][2], B0[2][2], B1[2][2];
;     const char* cA = (const char*)g.A + (size_t)cur.pm * tstep; const char* cB = (const char*)g.Bt + (size_t)cur.pn * tstep;
;     S.a_ready(cur);
;     if constexpr (SP2) {
;         PG8_STAGE(PG8_SB(0, 0), cB, voffB); PG8_STAGE(PG8_SB(0, 1), cB + hstep, voffB); PG8_STAGE(PG8_SA(0, 0), cA, voffA); PG8_STAGE(PG8_SA(0, 1), cA + hstep, voffA);
;         if (wr == 1) PG8_BAR;
; __device__ __forceinline__ void xcd_barrier(const XcdBarrier& b) {
;     ...
;             asm volatile("s_waitcnt vmcnt(0)" ::: "memory");
;         } else {
;             XB_SPIN(xb_ld(&bar[XB_XGEN(b.x)]) == gen, bar);
;             __builtin_amdgcn_fence(__ATOMIC_ACQUIRE, "agent");
;             asm volatile("s_waitcnt vmcnt(0)" ::: "memory");
;         }
;     }
;     __syncthreads();
.LBB0_760:
	s_or_b64 exec, exec, s[8:9]
.LBB0_761:
	s_or_b64 exec, exec, s[0:1]
	s_add_u32 s4, s38, 0x10800
	s_addc_u32 s5, s39, 0
	v_readlane_b32 s0, v255, 37
	s_add_u32 s26, s0, 0x900000
	v_readlane_b32 s0, v255, 38
	s_addc_u32 s58, s0, 0
	v_readlane_b32 s0, v255, 39
	v_mov_b32_e32 v25, v184
	v_readlane_b32 s1, v255, 40
	s_waitcnt lgkmcnt(0)
	s_barrier
	s_and_b64 vcc, exec, s[0:1]
	v_readfirstlane_b32 s8, v25
	s_cbranch_vccnz .LBB0_797
	v_lshlrev_b32_e32 v0, 4, v25
	v_add_u32_e32 v2, 0x2000, v0
	v_ashrrev_i32_e32 v3, 31, v2
	v_lshrrev_b32_e32 v3, 22, v3
	v_add_u32_e32 v3, v2, v3
	v_ashrrev_i32_e32 v24, 10, v3
	v_mul_i32_i24_e32 v3, 0x400, v24
	v_sub_u32_e32 v2, v2, v3
	v_lshrrev_b32_e32 v3, 4, v2
	v_bitop3_b32 v2, v3, v2, 32 bitop3:0x6c
	v_ashrrev_i32_e32 v3, 31, v2
	v_lshrrev_b32_e32 v3, 26, v3
	v_add_u32_e32 v3, v2, v3
	v_lshlrev_b32_e32 v20, 3, v24
	v_ashrrev_i32_e32 v26, 6, v3
	v_and_b32_e32 v20, -16, v20
	v_add_u32_e32 v20, v26, v20
	v_and_b32_e32 v21, 3, v26
	s_mov_b32 s0, 0x1fffe0
	v_lshrrev_b32_e32 v22, 2, v20
	v_lshlrev_b32_e32 v23, 1, v20
	v_and_b32_e32 v3, 0xc0, v3
	v_and_or_b32 v21, v20, s0, v21
	v_and_b32_e32 v22, 4, v22
	v_and_b32_e32 v23, 24, v23
	v_sub_u32_e32 v2, v2, v3
	v_mov_b32_e32 v30, 1
	v_or3_b32 v21, v21, v22, v23
	v_lshlrev_b32_e32 v22, 5, v24
	v_ashrrev_i16_sdwa v2, v30, sext(v2) dst_sel:DWORD dst_unused:UNUSED_PAD src0_sel:DWORD src1_sel:BYTE_0
	v_and_b32_e32 v22, 32, v22
	v_bfe_i32 v27, v2, 0, 16
	v_add_lshl_u32 v3, v22, v27, 1
	v_lshl_add_u32 v2, v21, 11, v3
	v_lshl_add_u32 v172, v20, 11, v3
	v_bfe_i32 v3, v25, 27, 1
	v_lshrrev_b32_e32 v3, 22, v3
	v_add_u32_e32 v3, v0, v3
	v_and_b32_e32 v3, 0xfffffc00, v3
	v_sub_u32_e32 v0, v0, v3
	v_lshrrev_b32_e32 v3, 4, v0
	v_ashrrev_i32_e32 v20, 31, v25
	v_bitop3_b32 v0, v3, v0, 32 bitop3:0x6c
	v_lshrrev_b32_e32 v20, 26, v20
	v_ashrrev_i32_e32 v3, 31, v0
	v_add_u32_e32 v20, v25, v20
	v_lshrrev_b32_e32 v3, 26, v3
	v_ashrrev_i32_e32 v29, 6, v20
	v_add_u32_e32 v3, v0, v3
	v_lshlrev_b32_e32 v20, 3, v29
	v_ashrrev_i32_e32 v28, 6, v3
	v_and_b32_e32 v20, -16, v20
	v_add_u32_e32 v20, v28, v20
	v_and_b32_e32 v21, 3, v28
	v_lshrrev_b32_e32 v22, 2, v20
	v_lshlrev_b32_e32 v23, 1, v20
	v_and_b32_e32 v3, 0xc0, v3
	s_ashr_i32 s10, s8, 6
	v_and_or_b32 v21, v20, s0, v21
	v_and_b32_e32 v22, 4, v22
	v_and_b32_e32 v23, 24, v23
	v_sub_u32_e32 v0, v0, v3
	s_ashr_i32 s9, s8, 8
	s_lshl_b32 s59, s10, 10
	v_or3_b32 v21, v21, v22, v23
	v_lshlrev_b32_e32 v22, 5, v29
	v_ashrrev_i16_sdwa v0, v30, sext(v0) dst_sel:DWORD dst_unused:UNUSED_PAD src0_sel:DWORD src1_sel:BYTE_0
	v_readlane_b32 s0, v254, 41
	v_and_b32_e32 v22, 32, v22
	v_bfe_i32 v30, v0, 0, 16
	v_readlane_b32 s1, v254, 42
	s_add_u32 s0, s26, s0
	v_add_lshl_u32 v3, v22, v30, 1
	s_addc_u32 s1, s58, s1
	s_add_i32 s62, s59, 0
	v_lshl_add_u32 v0, v21, 11, v3
	s_add_i32 m0, s62, 0x10000
	v_lshl_add_u32 v174, v20, 11, v3
	global_load_lds_dwordx4 v0, s[0:1]
	s_add_i32 m0, s62, 0x12000
	s_add_u32 s6, s0, 0x40000
	global_load_lds_dwordx4 v2, s[0:1]
	s_addc_u32 s7, s1, 0
	s_add_i32 m0, s62, 0x14000
	s_add_i32 s63, s62, 0x2000
	global_load_lds_dwordx4 v0, s[6:7]
	s_add_i32 m0, s62, 0x16000
	s_add_i32 s66, s62, 0x4000
	global_load_lds_dwordx4 v2, s[6:7]
	v_readlane_b32 s6, v254, 43
	s_mov_b32 m0, s62
	v_readlane_b32 s7, v254, 44
	s_add_i32 s67, s62, 0x6000
	v_mov_b32_e32 v3, v1
	s_cmp_eq_u32 s9, 1
	v_lshl_add_u64 v[20:21], s[0:1], 0, v[0:1]
	v_lshl_add_u64 v[22:23], s[0:1], 0, v[2:3]
	global_load_lds_dwordx4 v174, s[6:7]
	s_mov_b32 m0, s63
	s_nop 0
	global_load_lds_dwordx4 v172, s[6:7]
	v_readlane_b32 s6, v254, 45
	s_mov_b32 m0, s66
	v_readlane_b32 s7, v254, 46
	s_nop 4
	global_load_lds_dwordx4 v174, s[6:7]
	s_mov_b32 m0, s67
	s_nop 0
	global_load_lds_dwordx4 v172, s[6:7]
	s_cselect_b64 s[6:7], -1, 0
	s_cmp_lg_u32 s9, 1
	s_cbranch_scc1 .LBB0_764
	s_barrier

; #define PG8_STAGE(bufoff, gbase, voff) do { _Pragma("unroll") for (int _i = 0; _i < 2; ++_i) \
;         __builtin_amdgcn_global_load_lds((const unsigned*)((const char*)(gbase) + (voff)[_i]), (PG8_LAS unsigned*)(lds + (bufoff) + ldsw + _i * 8192), 16, 0, 0); } while (0)
; #define PG8_BAR __builtin_amdgcn_s_barrier()
; __device__ __forceinline__ unsigned xb_ld(unsigned* p)              { return __hip_atomic_load(p, __ATOMIC_RELAXED, __HIP_MEMORY_SCOPE_AGENT); }
; template <class Epi, class Sched, bool ALIGN_EPI = false, bool SP2 = false>
; __device__ __forceinline__ void gemm_phase(PG8_LAS unsigned char* lds, const Gemm g, const Sched& S, const Epi& E) {
;     ...
;     for (int i = 0; i < 2; ++i) { int R, C; stage_rc(tid * 16 + i * 8192, R, C); const int Rb = Epi::PERM ? ((R & ~31) + perm32(R & 31)) : R;
;         voffA[i] = (unsigned)(R * K + C) * 2u; voffB[i] = (unsigned)(Rb * K + C) * 2u; }
;     const size_t kstep = (size_t)(BK * 2);
;     const size_t hstep = (size_t)HALF * K * 2;
;     const size_t tstep = 2 * hstep;
;     const unsigned ldsw = (unsigned)wid * 1024u;
;     const int aoff = lds_byte(wr * 64 + fr, fq * 8), boff = lds_byte(wc * 32 + fr, fq * 8);
;     ...
;     Unit cur, nxt; int ui = 0;
;     if (!S.next(0, cur)) return;
;     f32x4 acc[2][2][4][2];
; #pragma unroll
;     for (int a = 0; a < 2; ++a)
; #pragma unroll
;         for (int b = 0; b < 2; ++b)
; #pragma unroll
;             for (int m = 0; m < 4; ++m)
; #pragma unroll
;                 for (int n = 0; n < 2; ++n) acc[a][b][m][n] = (f32x4){0.f, 0.f, 0.f, 0.f};
;     bf16x8 At[4][2], B0[2][2], B1[2][2];
;     const char* cA = (const char*)g.A + (size_t)cur.pm * tstep; const char* cB = (const char*)g.Bt + (size_t)cur.pn * tstep;
;     S.a_ready(cur);
;     if constexpr (SP2) {
;         PG8_STAGE(PG8_SB(0, 0), cB, voffB); PG8_STAGE(PG8_SB(0, 1), cB + hstep, voffB); PG8_STAGE(PG8_SA(0, 0), cA, voffA); PG8_STAGE(PG8_SA(0, 1), cA + hstep, voffA);
;         if (wr == 1) PG8_BAR;
; __device__ __forceinline__ void xcd_barrier(const XcdBarrier& b) {
;     ...
;             asm volatile("s_waitcnt vmcnt(0)" ::: "memory");
;         } else {
;             XB_SPIN(xb_ld(&bar[XB_XGEN(b.x)]) == gen, bar);
;             __builtin_amdgcn_fence(__ATOMIC_ACQUIRE, "agent");
;             asm volatile("s_waitcnt vmcnt(0)" ::: "memory");
;         }
;     }
;     __syncthreads();
.LBB0_853:
	s_or_b64 exec, exec, s[10:11]
.LBB0_854:
	s_or_b64 exec, exec, s[0:1]
	v_readlane_b32 s0, v255, 37
	s_add_u32 s26, s0, 0xb00000
	v_readlane_b32 s0, v255, 38
	s_addc_u32 s56, s0, 0
	v_readlane_b32 s0, v253, 62
	v_mov_b32_e32 v20, v184
	v_readlane_b32 s1, v253, 63
	s_waitcnt lgkmcnt(0)
	s_barrier
	s_andn2_b64 vcc, exec, s[0:1]
	v_readfirstlane_b32 s8, v20
	s_cbranch_vccnz .LBB0_874
	v_lshlrev_b32_e32 v0, 4, v20
	v_add_u32_e32 v2, 0x2000, v0
	v_ashrrev_i32_e32 v3, 31, v2
	v_lshrrev_b32_e32 v3, 22, v3
	v_add_u32_e32 v3, v2, v3
	v_ashrrev_i32_e32 v21, 10, v3
	v_mul_i32_i24_e32 v3, 0x400, v21
	v_sub_u32_e32 v2, v2, v3
	v_lshrrev_b32_e32 v3, 4, v2
	v_bitop3_b32 v2, v3, v2, 32 bitop3:0x6c
	v_ashrrev_i32_e32 v3, 31, v2
	v_lshrrev_b32_e32 v3, 26, v3
	v_add_u32_e32 v3, v2, v3
	v_lshlrev_b32_e32 v23, 3, v21
	v_ashrrev_i32_e32 v22, 6, v3
	v_and_b32_e32 v23, -16, v23
	v_add_u32_e32 v24, v22, v23
	v_and_b32_e32 v23, 3, v22
	s_mov_b32 s0, 0x1fffe0
	v_lshrrev_b32_e32 v25, 2, v24
	v_lshlrev_b32_e32 v26, 1, v24
	v_and_b32_e32 v3, 0xc0, v3
	v_and_or_b32 v23, v24, s0, v23
	v_and_b32_e32 v25, 4, v25
	v_and_b32_e32 v26, 24, v26
	v_sub_u32_e32 v2, v2, v3
	v_mov_b32_e32 v30, 1
	v_or3_b32 v25, v23, v25, v26
	v_lshlrev_b32_e32 v23, 5, v21
	v_ashrrev_i16_sdwa v2, v30, sext(v2) dst_sel:DWORD dst_unused:UNUSED_PAD src0_sel:DWORD src1_sel:BYTE_0
	v_and_b32_e32 v26, 32, v23
	v_bfe_i32 v23, v2, 0, 16
	v_add_lshl_u32 v3, v26, v23, 1
	v_lshl_add_u32 v2, v25, 11, v3
	v_lshl_add_u32 v148, v24, 11, v3
	v_bfe_i32 v3, v20, 27, 1
	v_lshrrev_b32_e32 v3, 22, v3
	v_add_u32_e32 v3, v0, v3
	v_and_b32_e32 v3, 0xfffffc00, v3
	v_sub_u32_e32 v0, v0, v3
	v_lshrrev_b32_e32 v3, 4, v0
	v_ashrrev_i32_e32 v25, 31, v20
	v_bitop3_b32 v0, v3, v0, 32 bitop3:0x6c
	v_lshrrev_b32_e32 v25, 26, v25
	v_ashrrev_i32_e32 v3, 31, v0
	v_add_u32_e32 v25, v20, v25
	v_lshrrev_b32_e32 v3, 26, v3
	v_ashrrev_i32_e32 v25, 6, v25
	v_add_u32_e32 v3, v0, v3
	v_lshlrev_b32_e32 v26, 3, v25
	v_ashrrev_i32_e32 v24, 6, v3
	v_and_b32_e32 v26, -16, v26
	v_add_u32_e32 v27, v24, v26
	v_and_b32_e32 v26, 3, v24
	v_lshrrev_b32_e32 v28, 2, v27
	v_lshlrev_b32_e32 v29, 1, v27
	v_and_b32_e32 v3, 0xc0, v3
	s_ashr_i32 s10, s8, 6
	v_and_or_b32 v26, v27, s0, v26
	v_and_b32_e32 v28, 4, v28
	v_and_b32_e32 v29, 24, v29
	v_sub_u32_e32 v0, v0, v3
	s_ashr_i32 s9, s8, 8
	s_lshl_b32 s57, s10, 10
	v_or3_b32 v28, v26, v28, v29
	v_lshlrev_b32_e32 v26, 5, v25
	v_ashrrev_i16_sdwa v0, v30, sext(v0) dst_sel:DWORD dst_unused:UNUSED_PAD src0_sel:DWORD src1_sel:BYTE_0
	v_readlane_b32 s0, v254, 25
	v_and_b32_e32 v29, 32, v26
	v_bfe_i32 v26, v0, 0, 16
	v_readlane_b32 s1, v254, 26
	s_add_u32 s0, s26, s0
	v_add_lshl_u32 v3, v29, v26, 1
	s_addc_u32 s1, s56, s1
	s_add_i32 s58, s57, 0
	v_lshl_add_u32 v0, v28, 11, v3
	s_add_i32 m0, s58, 0x10000
	v_lshl_add_u32 v150, v27, 11, v3
	global_load_lds_dwordx4 v0, s[0:1]
	s_add_i32 m0, s58, 0x12000
	s_add_u32 s6, s0, 0x40000
	global_load_lds_dwordx4 v2, s[0:1]
	s_addc_u32 s7, s1, 0
	s_add_i32 m0, s58, 0x14000
	s_add_i32 s59, s58, 0x2000
	global_load_lds_dwordx4 v0, s[6:7]
	s_add_i32 m0, s58, 0x16000
	s_add_i32 s62, s58, 0x4000
	global_load_lds_dwordx4 v2, s[6:7]
	v_readlane_b32 s6, v254, 29
	s_mov_b32 m0, s58
	v_readlane_b32 s7, v254, 30
	s_add_i32 s63, s58, 0x6000
	s_cmp_eq_u32 s9, 1
	s_nop 2
	global_load_lds_dwordx4 v150, s[6:7]
	s_mov_b32 m0, s59
	s_nop 0
	global_load_lds_dwordx4 v148, s[6:7]
	v_readlane_b32 s6, v254, 31
	s_mov_b32 m0, s62
	v_readlane_b32 s7, v254, 32
	s_nop 4
	global_load_lds_dwordx4 v150, s[6:7]
	s_mov_b32 m0, s63
	s_nop 0
	global_load_lds_dwordx4 v148, s[6:7]
	s_cselect_b64 s[6:7], -1, 0
	s_cmp_lg_u32 s9, 1
	s_cbranch_scc1 .LBB0_857
	s_barrier

; #define PG8_STAGE(bufoff, gbase, voff) do { _Pragma("unroll") for (int _i = 0; _i < 2; ++_i) \
;         __builtin_amdgcn_global_load_lds((const unsigned*)((const char*)(gbase) + (voff)[_i]), (PG8_LAS unsigned*)(lds + (bufoff) + ldsw + _i * 8192), 16, 0, 0); } while (0)
; #define PG8_BAR __builtin_amdgcn_s_barrier()
; __device__ __forceinline__ unsigned xb_ld(unsigned* p)              { return __hip_atomic_load(p, __ATOMIC_RELAXED, __HIP_MEMORY_SCOPE_AGENT); }
; template <class Epi, class Sched, bool ALIGN_EPI = false, bool SP2 = false>
; __device__ __forceinline__ void gemm_phase(PG8_LAS unsigned char* lds, const Gemm g, const Sched& S, const Epi& E) {
;     ...
;     for (int i = 0; i < 2; ++i) { int R, C; stage_rc(tid * 16 + i * 8192, R, C); const int Rb = Epi::PERM ? ((R & ~31) + perm32(R & 31)) : R;
;         voffA[i] = (unsigned)(R * K + C) * 2u; voffB[i] = (unsigned)(Rb * K + C) * 2u; }
;     const size_t kstep = (size_t)(BK * 2);
;     const size_t hstep = (size_t)HALF * K * 2;
;     const size_t tstep = 2 * hstep;
;     const unsigned ldsw = (unsigned)wid * 1024u;
;     const int aoff = lds_byte(wr * 64 + fr, fq * 8), boff = lds_byte(wc * 32 + fr, fq * 8);
;     ...
;     Unit cur, nxt; int ui = 0;
;     if (!S.next(0, cur)) return;
;     f32x4 acc[2][2][4][2];
; #pragma unroll
;     for (int a = 0; a < 2; ++a)
; #pragma unroll
;         for (int b = 0; b < 2; ++b)
; #pragma unroll
;             for (int m = 0; m < 4; ++m)
; #pragma unroll
;                 for (int n = 0; n < 2; ++n) acc[a][b][m][n] = (f32x4){0.f, 0.f, 0.f, 0.f};
;     bf16x8 At[4][2], B0[2][2], B1[2][2];
;     const char* cA = (const char*)g.A + (size_t)cur.pm * tstep; const char* cB = (const char*)g.Bt + (size_t)cur.pn * tstep;
;     S.a_ready(cur);
;     if constexpr (SP2) {
;         PG8_STAGE(PG8_SB(0, 0), cB, voffB); PG8_STAGE(PG8_SB(0, 1), cB + hstep, voffB); PG8_STAGE(PG8_SA(0, 0), cA, voffA); PG8_STAGE(PG8_SA(0, 1), cA + hstep, voffA);
;         if (wr == 1) PG8_BAR;
; __device__ __forceinline__ void xcd_barrier(const XcdBarrier& b) {
;     ...
;             asm volatile("s_waitcnt vmcnt(0)" ::: "memory");
;         } else {
;             XB_SPIN(xb_ld(&bar[XB_XGEN(b.x)]) == gen, bar);
;             __builtin_amdgcn_fence(__ATOMIC_ACQUIRE, "agent");
;             asm volatile("s_waitcnt vmcnt(0)" ::: "memory");
;         }
;     }
;     __syncthreads();
.LBB0_928:
	s_or_b64 exec, exec, s[8:9]
.LBB0_929:
	s_or_b64 exec, exec, s[0:1]
	s_add_u32 s14, s38, 0x21000
	v_readlane_b32 s0, v255, 25
	s_addc_u32 s15, s39, 0
	v_readlane_b32 s1, v255, 26
	s_and_b64 s[0:1], s[0:1], exec
	v_readlane_b32 s0, v255, 39
	v_mov_b32_e32 v24, v184
	v_readlane_b32 s1, v255, 40
	s_waitcnt lgkmcnt(0)
	s_barrier
	s_cselect_b32 s17, 0, s69
	s_cselect_b32 s16, 0, s68
	s_and_b64 vcc, exec, s[0:1]
	v_readfirstlane_b32 s4, v24
	s_cbranch_vccnz .LBB0_1029
	v_lshlrev_b32_e32 v0, 4, v24
	v_add_u32_e32 v2, 0x2000, v0
	v_ashrrev_i32_e32 v3, 31, v2
	v_lshrrev_b32_e32 v3, 22, v3
	v_add_u32_e32 v3, v2, v3
	v_ashrrev_i32_e32 v25, 10, v3
	v_mul_i32_i24_e32 v3, 0x400, v25
	v_sub_u32_e32 v2, v2, v3
	v_lshrrev_b32_e32 v3, 4, v2
	v_bitop3_b32 v2, v3, v2, 32 bitop3:0x6c
	v_ashrrev_i32_e32 v3, 31, v2
	v_lshrrev_b32_e32 v3, 26, v3
	v_add_u32_e32 v3, v2, v3
	v_lshlrev_b32_e32 v20, 3, v25
	v_readlane_b32 s0, v255, 37
	v_ashrrev_i32_e32 v26, 6, v3
	v_and_b32_e32 v20, -16, v20
	s_add_u32 s26, s0, 0x1300000
	v_readlane_b32 s0, v255, 38
	v_add_u32_e32 v20, v26, v20
	s_addc_u32 s66, s0, 0
	v_and_b32_e32 v21, 3, v26
	s_mov_b32 s0, 0x7ffe0
	v_lshrrev_b32_e32 v22, 2, v20
	v_lshlrev_b32_e32 v23, 1, v20
	v_and_b32_e32 v3, 0xc0, v3
	v_and_or_b32 v21, v20, s0, v21
	v_and_b32_e32 v22, 4, v22
	v_and_b32_e32 v23, 24, v23
	v_sub_u32_e32 v2, v2, v3
	v_mov_b32_e32 v30, 1
	v_or3_b32 v21, v21, v22, v23
	v_lshlrev_b32_e32 v22, 5, v25
	v_ashrrev_i16_sdwa v2, v30, sext(v2) dst_sel:DWORD dst_unused:UNUSED_PAD src0_sel:DWORD src1_sel:BYTE_0
	v_and_b32_e32 v22, 32, v22
	v_bfe_i32 v27, v2, 0, 16
	v_add_lshl_u32 v3, v22, v27, 1
	v_lshl_add_u32 v2, v21, 13, v3
	v_lshl_add_u32 v176, v20, 13, v3
	v_bfe_i32 v3, v24, 27, 1
	v_lshrrev_b32_e32 v3, 22, v3
	v_add_u32_e32 v3, v0, v3
	v_and_b32_e32 v3, 0xfffffc00, v3
	v_sub_u32_e32 v0, v0, v3
	v_lshrrev_b32_e32 v3, 4, v0
	v_ashrrev_i32_e32 v20, 31, v24
	v_bitop3_b32 v0, v3, v0, 32 bitop3:0x6c
	v_lshrrev_b32_e32 v20, 26, v20
	v_ashrrev_i32_e32 v3, 31, v0
	v_add_u32_e32 v20, v24, v20
	v_lshrrev_b32_e32 v3, 26, v3
	v_ashrrev_i32_e32 v29, 6, v20
	v_add_u32_e32 v3, v0, v3
	v_lshlrev_b32_e32 v20, 3, v29
	v_ashrrev_i32_e32 v28, 6, v3
	v_and_b32_e32 v20, -16, v20
	v_add_u32_e32 v20, v28, v20
	v_and_b32_e32 v21, 3, v28
	v_lshrrev_b32_e32 v22, 2, v20
	v_lshlrev_b32_e32 v23, 1, v20
	v_and_b32_e32 v3, 0xc0, v3
	s_ashr_i32 s6, s4, 6
	v_and_or_b32 v21, v20, s0, v21
	v_and_b32_e32 v22, 4, v22
	v_and_b32_e32 v23, 24, v23
	v_sub_u32_e32 v0, v0, v3
	s_ashr_i32 s5, s4, 8
	s_lshl_b32 s67, s6, 10
	v_or3_b32 v21, v21, v22, v23
	v_lshlrev_b32_e32 v22, 5, v29
	v_ashrrev_i16_sdwa v0, v30, sext(v0) dst_sel:DWORD dst_unused:UNUSED_PAD src0_sel:DWORD src1_sel:BYTE_0
	v_readlane_b32 s0, v254, 47
	v_and_b32_e32 v22, 32, v22
	v_bfe_i32 v30, v0, 0, 16
	v_readlane_b32 s1, v254, 48
	s_add_u32 s0, s26, s0
	v_add_lshl_u32 v3, v22, v30, 1
	s_addc_u32 s1, s66, s1
	s_add_i32 s72, s67, 0
	v_lshl_add_u32 v0, v21, 13, v3
	s_add_i32 m0, s72, 0x10000
	v_lshl_add_u32 v178, v20, 13, v3
	global_load_lds_dwordx4 v0, s[0:1]
	s_add_i32 m0, s72, 0x12000
	s_add_u32 s8, s0, 0x100000
	global_load_lds_dwordx4 v2, s[0:1]
	s_addc_u32 s9, s1, 0
	s_add_i32 m0, s72, 0x14000
	s_add_i32 s73, s72, 0x2000
	global_load_lds_dwordx4 v0, s[8:9]
	s_add_i32 m0, s72, 0x16000
	s_add_i32 s74, s72, 0x4000
	global_load_lds_dwordx4 v2, s[8:9]
	v_readlane_b32 s8, v254, 51
	s_mov_b32 m0, s72
	v_readlane_b32 s9, v254, 52
	s_add_i32 s75, s72, 0x6000
	v_mov_b32_e32 v3, v1
	s_cmp_eq_u32 s5, 1
	v_lshl_add_u64 v[20:21], s[0:1], 0, v[0:1]
	s_cselect_b64 s[18:19], -1, 0
	global_load_lds_dwordx4 v178, s[8:9]
	s_mov_b32 m0, s73
	s_cmp_lg_u32 s5, 1
	global_load_lds_dwordx4 v176, s[8:9]
	v_readlane_b32 s8, v254, 53
	s_mov_b32 m0, s74
	v_readlane_b32 s9, v254, 54
	v_lshl_add_u64 v[22:23], s[0:1], 0, v[2:3]
	s_nop 3
	global_load_lds_dwordx4 v178, s[8:9]
	s_mov_b32 m0, s75
	s_nop 0
	global_load_lds_dwordx4 v176, s[8:9]
	s_cbranch_scc1 .LBB0_932
	s_barrier
